# v11 + P7 chained-GEMM epilogues: dummy dword loads warm all 16 iterations' gate lines in L2 at the start of the mid and final epilogue
# baseline (speedup 1.0000x reference)
.LBB0_1229:
	s_cmp_lg_u32 s39, 0
	s_cselect_b64 s[52:53], -1, 0
	s_lshl_b32 s19, s54, 8
	v_add_u32_e32 v4, s19, v1
	s_and_b64 vcc, exec, s[52:53]
	v_lshl_or_b32 v154, s38, 8, v168
	v_or_b32_e32 v160, 16, v4
	v_or_b32_e32 v152, 32, v4
	v_or_b32_e32 v150, 48, v4
	s_cbranch_vccz .LBB0_1237
	v_mov_b64_e32 v[166:167], s[46:47]
	v_mad_i64_i32 v[156:157], s[38:39], v4, s73, v[166:167]
	v_ashrrev_i32_e32 v155, 31, v154
	v_lshl_add_u64 v[174:175], v[156:157], 0, s[14:15]
	v_lshlrev_b64 v[156:157], 1, v[154:155]
	v_lshl_add_u64 v[158:159], v[174:175], 0, v[156:157]
	global_load_dwordx4 v[170:173], v[158:159], off
	s_mov_b32 s76, 0xa4000
	s_mov_b32 s77, 0
	s_mov_b32 s78, 0x334000
	s_mov_b32 s79, 0
	global_load_dword v202, v[158:159], off offset:256
	v_mov_b64_e32 v[204:205], v[158:159]
	v_lshl_add_u64 v[204:205], v[204:205], 0, s[76:77]
	global_load_dword v202, v[204:205], off
	global_load_dword v202, v[204:205], off offset:256
	v_lshl_add_u64 v[204:205], v[204:205], 0, s[76:77]
	global_load_dword v202, v[204:205], off
	global_load_dword v202, v[204:205], off offset:256
	v_lshl_add_u64 v[204:205], v[204:205], 0, s[76:77]
	global_load_dword v202, v[204:205], off
	global_load_dword v202, v[204:205], off offset:256
	v_lshl_add_u64 v[204:205], v[204:205], 0, s[78:79]
	global_load_dword v202, v[204:205], off
	global_load_dword v202, v[204:205], off offset:256
	v_lshl_add_u64 v[204:205], v[204:205], 0, s[76:77]
	global_load_dword v202, v[204:205], off
	global_load_dword v202, v[204:205], off offset:256
	v_lshl_add_u64 v[204:205], v[204:205], 0, s[76:77]
	global_load_dword v202, v[204:205], off
	global_load_dword v202, v[204:205], off offset:256
	v_lshl_add_u64 v[204:205], v[204:205], 0, s[76:77]
	global_load_dword v202, v[204:205], off
	global_load_dword v202, v[204:205], off offset:256
	v_ashrrev_i32_e32 v5, 31, v4
	v_lshlrev_b64 v[176:177], 13, v[4:5]
	v_or_b32_e32 v158, 0x80, v154
	v_ashrrev_i32_e32 v159, 31, v158
	v_lshl_add_u64 v[176:177], s[28:29], 0, v[176:177]
	v_lshlrev_b64 v[158:159], 1, v[158:159]
	v_lshl_add_u64 v[176:177], v[176:177], 0, v[156:157]
	v_lshl_add_u64 v[174:175], v[174:175], 0, v[158:159]
	s_waitcnt vmcnt(0)
	v_lshlrev_b32_e32 v3, 16, v170
	v_and_b32_e32 v5, 0xffff0000, v170
	v_lshlrev_b32_e32 v151, 16, v171
	v_and_b32_e32 v153, 0xffff0000, v171
	v_lshlrev_b32_e32 v155, 16, v172
	v_and_b32_e32 v161, 0xffff0000, v172
	v_lshlrev_b32_e32 v170, 16, v173
	v_and_b32_e32 v171, 0xffff0000, v173
	v_mul_f32_e32 v3, 0xbfb8aa3b, v3
	v_mul_f32_e32 v5, 0xbfb8aa3b, v5
	v_mul_f32_e32 v151, 0xbfb8aa3b, v151
	v_mul_f32_e32 v153, 0xbfb8aa3b, v153
	v_mul_f32_e32 v155, 0xbfb8aa3b, v155
	v_mul_f32_e32 v161, 0xbfb8aa3b, v161
	v_mul_f32_e32 v170, 0xbfb8aa3b, v170
	v_mul_f32_e32 v171, 0xbfb8aa3b, v171
	v_exp_f32_e32 v3, v3
	v_exp_f32_e32 v5, v5
	v_exp_f32_e32 v151, v151
	v_exp_f32_e32 v153, v153
	v_exp_f32_e32 v155, v155
	v_exp_f32_e32 v161, v161
	v_exp_f32_e32 v170, v170
	v_exp_f32_e32 v171, v171
	v_add_f32_e32 v3, 1.0, v3
	v_add_f32_e32 v5, 1.0, v5
	v_add_f32_e32 v151, 1.0, v151
	v_add_f32_e32 v153, 1.0, v153
	v_add_f32_e32 v155, 1.0, v155
	v_add_f32_e32 v161, 1.0, v161
	v_add_f32_e32 v179, 1.0, v170
	v_add_f32_e32 v181, 1.0, v171
	v_rcp_f32_e32 v170, v3
	v_rcp_f32_e32 v171, v5
	v_rcp_f32_e32 v172, v151
	v_rcp_f32_e32 v173, v153
	v_rcp_f32_e32 v178, v155
	v_rcp_f32_e32 v180, v179
	v_rcp_f32_e32 v181, v181
	v_rcp_f32_e32 v179, v161
	v_pk_mul_f32 v[172:173], v[132:133], v[172:173]
	v_pk_mul_f32 v[170:171], v[130:131], v[170:171]
	v_pk_mul_f32 v[180:181], v[128:129], v[180:181]
	v_pk_mul_f32 v[178:179], v[126:127], v[178:179]
	v_cvt_pk_bf16_f32 v170, v170, v171
	v_cvt_pk_bf16_f32 v171, v172, v173
	s_nop 0
	v_cvt_pk_bf16_f32 v172, v178, v179
	v_cvt_pk_bf16_f32 v173, v180, v181
	global_store_dwordx4 v[176:177], v[170:173], off
	global_load_dwordx4 v[170:173], v[174:175], off
	v_mad_i64_i32 v[174:175], s[38:39], v160, s73, v[166:167]
	v_lshl_add_u64 v[174:175], v[174:175], 0, s[14:15]
	v_lshl_add_u64 v[178:179], v[174:175], 0, v[156:157]
	v_lshl_add_u64 v[174:175], v[174:175], 0, v[158:159]
	s_waitcnt vmcnt(0)
	v_lshlrev_b32_e32 v3, 16, v170
	v_and_b32_e32 v5, 0xffff0000, v170
	v_lshlrev_b32_e32 v151, 16, v171
	v_and_b32_e32 v153, 0xffff0000, v171
	v_lshlrev_b32_e32 v155, 16, v172
	v_and_b32_e32 v161, 0xffff0000, v172
	v_lshlrev_b32_e32 v170, 16, v173
	v_and_b32_e32 v171, 0xffff0000, v173
	v_mul_f32_e32 v3, 0xbfb8aa3b, v3
	v_mul_f32_e32 v5, 0xbfb8aa3b, v5
	v_mul_f32_e32 v151, 0xbfb8aa3b, v151
	v_mul_f32_e32 v153, 0xbfb8aa3b, v153
	v_mul_f32_e32 v155, 0xbfb8aa3b, v155
	v_mul_f32_e32 v161, 0xbfb8aa3b, v161
	v_mul_f32_e32 v170, 0xbfb8aa3b, v170
	v_mul_f32_e32 v171, 0xbfb8aa3b, v171
	v_exp_f32_e32 v3, v3
	v_exp_f32_e32 v5, v5
	v_exp_f32_e32 v151, v151
	v_exp_f32_e32 v153, v153
	v_exp_f32_e32 v155, v155
	v_exp_f32_e32 v161, v161
	v_exp_f32_e32 v170, v170
	v_exp_f32_e32 v171, v171
	v_add_f32_e32 v3, 1.0, v3
	v_add_f32_e32 v5, 1.0, v5
	v_add_f32_e32 v151, 1.0, v151
	v_add_f32_e32 v153, 1.0, v153
	v_add_f32_e32 v155, 1.0, v155
	v_add_f32_e32 v161, 1.0, v161
	v_add_f32_e32 v181, 1.0, v170
	v_add_f32_e32 v183, 1.0, v171
	v_rcp_f32_e32 v170, v3
	v_rcp_f32_e32 v171, v5
	v_rcp_f32_e32 v172, v151
	v_rcp_f32_e32 v173, v153
	v_rcp_f32_e32 v180, v155
	v_rcp_f32_e32 v182, v181
	v_rcp_f32_e32 v183, v183
	v_rcp_f32_e32 v181, v161
	v_pk_mul_f32 v[172:173], v[100:101], v[172:173]
	v_pk_mul_f32 v[170:171], v[98:99], v[170:171]
	v_pk_mul_f32 v[182:183], v[96:97], v[182:183]
	v_pk_mul_f32 v[180:181], v[94:95], v[180:181]
	v_cvt_pk_bf16_f32 v170, v170, v171
	v_cvt_pk_bf16_f32 v171, v172, v173
	v_ashrrev_i32_e32 v161, 31, v160
	v_cvt_pk_bf16_f32 v172, v180, v181
	v_cvt_pk_bf16_f32 v173, v182, v183
	global_store_dwordx4 v[176:177], v[170:173], off offset:256
	global_load_dwordx4 v[170:173], v[178:179], off
	v_lshlrev_b64 v[176:177], 13, v[160:161]
	v_lshl_add_u64 v[176:177], s[28:29], 0, v[176:177]
	v_lshl_add_u64 v[176:177], v[176:177], 0, v[156:157]
	s_waitcnt vmcnt(0)
	v_lshlrev_b32_e32 v3, 16, v170
	v_and_b32_e32 v5, 0xffff0000, v170
	v_lshlrev_b32_e32 v151, 16, v171
	v_and_b32_e32 v153, 0xffff0000, v171
	v_lshlrev_b32_e32 v155, 16, v172
	v_and_b32_e32 v161, 0xffff0000, v172
	v_lshlrev_b32_e32 v170, 16, v173
	v_and_b32_e32 v171, 0xffff0000, v173
	v_mul_f32_e32 v3, 0xbfb8aa3b, v3
	v_mul_f32_e32 v5, 0xbfb8aa3b, v5
	v_mul_f32_e32 v151, 0xbfb8aa3b, v151
	v_mul_f32_e32 v153, 0xbfb8aa3b, v153
	v_mul_f32_e32 v155, 0xbfb8aa3b, v155
	v_mul_f32_e32 v161, 0xbfb8aa3b, v161
	v_mul_f32_e32 v170, 0xbfb8aa3b, v170
	v_mul_f32_e32 v171, 0xbfb8aa3b, v171
	v_exp_f32_e32 v3, v3
	v_exp_f32_e32 v5, v5
	v_exp_f32_e32 v151, v151
	v_exp_f32_e32 v153, v153
	v_exp_f32_e32 v155, v155
	v_exp_f32_e32 v161, v161
	v_exp_f32_e32 v170, v170
	v_exp_f32_e32 v171, v171
	v_add_f32_e32 v3, 1.0, v3
	v_add_f32_e32 v5, 1.0, v5
	v_add_f32_e32 v151, 1.0, v151
	v_add_f32_e32 v153, 1.0, v153
	v_add_f32_e32 v155, 1.0, v155
	v_add_f32_e32 v161, 1.0, v161
	v_add_f32_e32 v179, 1.0, v170
	v_add_f32_e32 v181, 1.0, v171
	v_rcp_f32_e32 v170, v3
	v_rcp_f32_e32 v171, v5
	v_rcp_f32_e32 v172, v151
	v_rcp_f32_e32 v173, v153
	v_rcp_f32_e32 v178, v155
	v_rcp_f32_e32 v180, v179
	v_rcp_f32_e32 v181, v181
	v_rcp_f32_e32 v179, v161
	v_pk_mul_f32 v[172:173], v[124:125], v[172:173]
	v_pk_mul_f32 v[170:171], v[122:123], v[170:171]
	v_pk_mul_f32 v[180:181], v[120:121], v[180:181]
	v_pk_mul_f32 v[178:179], v[118:119], v[178:179]
	v_cvt_pk_bf16_f32 v170, v170, v171
	v_cvt_pk_bf16_f32 v171, v172, v173
	s_nop 0
	v_cvt_pk_bf16_f32 v172, v178, v179
	v_cvt_pk_bf16_f32 v173, v180, v181
	global_store_dwordx4 v[176:177], v[170:173], off
	global_load_dwordx4 v[170:173], v[174:175], off
	v_mad_i64_i32 v[174:175], s[38:39], v152, s73, v[166:167]
	v_lshl_add_u64 v[174:175], v[174:175], 0, s[14:15]
	v_lshl_add_u64 v[178:179], v[174:175], 0, v[156:157]
	v_lshl_add_u64 v[174:175], v[174:175], 0, v[158:159]
	s_waitcnt vmcnt(0)
	v_lshlrev_b32_e32 v3, 16, v170
	v_and_b32_e32 v5, 0xffff0000, v170
	v_lshlrev_b32_e32 v151, 16, v171
	v_and_b32_e32 v153, 0xffff0000, v171
	v_lshlrev_b32_e32 v155, 16, v172
	v_and_b32_e32 v161, 0xffff0000, v172
	v_lshlrev_b32_e32 v170, 16, v173
	v_and_b32_e32 v171, 0xffff0000, v173
	v_mul_f32_e32 v3, 0xbfb8aa3b, v3
	v_mul_f32_e32 v5, 0xbfb8aa3b, v5
	v_mul_f32_e32 v151, 0xbfb8aa3b, v151
	v_mul_f32_e32 v153, 0xbfb8aa3b, v153
	v_mul_f32_e32 v155, 0xbfb8aa3b, v155
	v_mul_f32_e32 v161, 0xbfb8aa3b, v161
	v_mul_f32_e32 v170, 0xbfb8aa3b, v170
	v_mul_f32_e32 v171, 0xbfb8aa3b, v171
	v_exp_f32_e32 v3, v3
	v_exp_f32_e32 v5, v5
	v_exp_f32_e32 v151, v151
	v_exp_f32_e32 v153, v153
	v_exp_f32_e32 v155, v155
	v_exp_f32_e32 v161, v161
	v_exp_f32_e32 v170, v170
	v_exp_f32_e32 v171, v171
	v_add_f32_e32 v3, 1.0, v3
	v_add_f32_e32 v5, 1.0, v5
	v_add_f32_e32 v151, 1.0, v151
	v_add_f32_e32 v153, 1.0, v153
	v_add_f32_e32 v155, 1.0, v155
	v_add_f32_e32 v161, 1.0, v161
	v_add_f32_e32 v181, 1.0, v170
	v_add_f32_e32 v183, 1.0, v171
	v_rcp_f32_e32 v170, v3
	v_rcp_f32_e32 v171, v5
	v_rcp_f32_e32 v172, v151
	v_rcp_f32_e32 v173, v153
	v_rcp_f32_e32 v180, v155
	v_rcp_f32_e32 v182, v181
	v_rcp_f32_e32 v183, v183
	v_rcp_f32_e32 v181, v161
	v_pk_mul_f32 v[172:173], v[92:93], v[172:173]
	v_pk_mul_f32 v[170:171], v[90:91], v[170:171]
	v_pk_mul_f32 v[182:183], v[88:89], v[182:183]
	v_pk_mul_f32 v[180:181], v[86:87], v[180:181]
	v_cvt_pk_bf16_f32 v170, v170, v171
	v_cvt_pk_bf16_f32 v171, v172, v173
	v_ashrrev_i32_e32 v153, 31, v152
	v_cvt_pk_bf16_f32 v172, v180, v181
	v_cvt_pk_bf16_f32 v173, v182, v183
	global_store_dwordx4 v[176:177], v[170:173], off offset:256
	global_load_dwordx4 v[170:173], v[178:179], off
	v_lshlrev_b64 v[176:177], 13, v[152:153]
	v_lshl_add_u64 v[176:177], s[28:29], 0, v[176:177]
	v_lshl_add_u64 v[176:177], v[176:177], 0, v[156:157]
	s_waitcnt vmcnt(0)
	v_lshlrev_b32_e32 v3, 16, v170
	v_and_b32_e32 v5, 0xffff0000, v170
	v_lshlrev_b32_e32 v151, 16, v171
	v_and_b32_e32 v153, 0xffff0000, v171
	v_lshlrev_b32_e32 v155, 16, v172
	v_and_b32_e32 v161, 0xffff0000, v172
	v_lshlrev_b32_e32 v170, 16, v173
	v_and_b32_e32 v171, 0xffff0000, v173
	v_mul_f32_e32 v3, 0xbfb8aa3b, v3
	v_mul_f32_e32 v5, 0xbfb8aa3b, v5
	v_mul_f32_e32 v151, 0xbfb8aa3b, v151
	v_mul_f32_e32 v153, 0xbfb8aa3b, v153
	v_mul_f32_e32 v155, 0xbfb8aa3b, v155
	v_mul_f32_e32 v161, 0xbfb8aa3b, v161
	v_mul_f32_e32 v170, 0xbfb8aa3b, v170
	v_mul_f32_e32 v171, 0xbfb8aa3b, v171
	v_exp_f32_e32 v3, v3
	v_exp_f32_e32 v5, v5
	v_exp_f32_e32 v151, v151
	v_exp_f32_e32 v153, v153
	v_exp_f32_e32 v155, v155
	v_exp_f32_e32 v161, v161
	v_exp_f32_e32 v170, v170
	v_exp_f32_e32 v171, v171
	v_add_f32_e32 v3, 1.0, v3
	v_add_f32_e32 v5, 1.0, v5
	v_add_f32_e32 v151, 1.0, v151
	v_add_f32_e32 v153, 1.0, v153
	v_add_f32_e32 v155, 1.0, v155
	v_add_f32_e32 v161, 1.0, v161
	v_add_f32_e32 v179, 1.0, v170
	v_add_f32_e32 v181, 1.0, v171
	v_rcp_f32_e32 v170, v3
	v_rcp_f32_e32 v171, v5
	v_rcp_f32_e32 v172, v151
	v_rcp_f32_e32 v173, v153
	v_rcp_f32_e32 v178, v155
	v_rcp_f32_e32 v180, v179
	v_rcp_f32_e32 v181, v181
	v_rcp_f32_e32 v179, v161
	v_pk_mul_f32 v[172:173], v[116:117], v[172:173]
	v_pk_mul_f32 v[170:171], v[114:115], v[170:171]
	v_pk_mul_f32 v[180:181], v[112:113], v[180:181]
	v_pk_mul_f32 v[178:179], v[110:111], v[178:179]
	v_cvt_pk_bf16_f32 v170, v170, v171
	v_cvt_pk_bf16_f32 v171, v172, v173
	s_nop 0
	v_cvt_pk_bf16_f32 v172, v178, v179
	v_cvt_pk_bf16_f32 v173, v180, v181
	global_store_dwordx4 v[176:177], v[170:173], off
	global_load_dwordx4 v[170:173], v[174:175], off
	v_mad_i64_i32 v[174:175], s[38:39], v150, s73, v[166:167]
	v_lshl_add_u64 v[174:175], v[174:175], 0, s[14:15]
	v_lshl_add_u64 v[178:179], v[174:175], 0, v[156:157]
	v_lshl_add_u64 v[174:175], v[174:175], 0, v[158:159]
	s_waitcnt vmcnt(0)
	v_lshlrev_b32_e32 v3, 16, v170
	v_and_b32_e32 v5, 0xffff0000, v170
	v_lshlrev_b32_e32 v151, 16, v171
	v_and_b32_e32 v153, 0xffff0000, v171
	v_lshlrev_b32_e32 v155, 16, v172
	v_and_b32_e32 v161, 0xffff0000, v172
	v_lshlrev_b32_e32 v170, 16, v173
	v_and_b32_e32 v171, 0xffff0000, v173
	v_mul_f32_e32 v3, 0xbfb8aa3b, v3
	v_mul_f32_e32 v5, 0xbfb8aa3b, v5
	v_mul_f32_e32 v151, 0xbfb8aa3b, v151
	v_mul_f32_e32 v153, 0xbfb8aa3b, v153
	v_mul_f32_e32 v155, 0xbfb8aa3b, v155
	v_mul_f32_e32 v161, 0xbfb8aa3b, v161
	v_mul_f32_e32 v170, 0xbfb8aa3b, v170
	v_mul_f32_e32 v171, 0xbfb8aa3b, v171
	v_exp_f32_e32 v3, v3
	v_exp_f32_e32 v5, v5
	v_exp_f32_e32 v151, v151
	v_exp_f32_e32 v153, v153
	v_exp_f32_e32 v155, v155
	v_exp_f32_e32 v161, v161
	v_exp_f32_e32 v170, v170
	v_exp_f32_e32 v171, v171
	v_add_f32_e32 v3, 1.0, v3
	v_add_f32_e32 v5, 1.0, v5
	v_add_f32_e32 v151, 1.0, v151
	v_add_f32_e32 v153, 1.0, v153
	v_add_f32_e32 v155, 1.0, v155
	v_add_f32_e32 v161, 1.0, v161
	v_add_f32_e32 v181, 1.0, v170
	v_add_f32_e32 v183, 1.0, v171
	v_rcp_f32_e32 v170, v3
	v_rcp_f32_e32 v171, v5
	v_rcp_f32_e32 v172, v151
	v_rcp_f32_e32 v173, v153
	v_rcp_f32_e32 v180, v155
	v_rcp_f32_e32 v182, v181
	v_rcp_f32_e32 v183, v183
	v_rcp_f32_e32 v181, v161
	v_pk_mul_f32 v[172:173], v[84:85], v[172:173]
	v_pk_mul_f32 v[170:171], v[82:83], v[170:171]
	v_pk_mul_f32 v[182:183], v[80:81], v[182:183]
	v_pk_mul_f32 v[180:181], v[78:79], v[180:181]
	v_cvt_pk_bf16_f32 v170, v170, v171
	v_cvt_pk_bf16_f32 v171, v172, v173
	v_ashrrev_i32_e32 v151, 31, v150
	v_cvt_pk_bf16_f32 v172, v180, v181
	v_cvt_pk_bf16_f32 v173, v182, v183
	global_store_dwordx4 v[176:177], v[170:173], off offset:256
	global_load_dwordx4 v[170:173], v[178:179], off
	v_lshlrev_b64 v[176:177], 13, v[150:151]
	v_lshl_add_u64 v[176:177], s[28:29], 0, v[176:177]
	v_lshl_add_u64 v[176:177], v[176:177], 0, v[156:157]
	s_waitcnt vmcnt(0)
	v_lshlrev_b32_e32 v3, 16, v170
	v_and_b32_e32 v5, 0xffff0000, v170
	v_lshlrev_b32_e32 v151, 16, v171
	v_and_b32_e32 v153, 0xffff0000, v171
	v_lshlrev_b32_e32 v155, 16, v172
	v_and_b32_e32 v161, 0xffff0000, v172
	v_lshlrev_b32_e32 v170, 16, v173
	v_and_b32_e32 v171, 0xffff0000, v173
	v_mul_f32_e32 v3, 0xbfb8aa3b, v3
	v_mul_f32_e32 v5, 0xbfb8aa3b, v5
	v_mul_f32_e32 v151, 0xbfb8aa3b, v151
	v_mul_f32_e32 v153, 0xbfb8aa3b, v153
	v_mul_f32_e32 v155, 0xbfb8aa3b, v155
	v_mul_f32_e32 v161, 0xbfb8aa3b, v161
	v_mul_f32_e32 v170, 0xbfb8aa3b, v170
	v_mul_f32_e32 v171, 0xbfb8aa3b, v171
	v_exp_f32_e32 v3, v3
	v_exp_f32_e32 v5, v5
	v_exp_f32_e32 v151, v151
	v_exp_f32_e32 v153, v153
	v_exp_f32_e32 v155, v155
	v_exp_f32_e32 v161, v161
	v_exp_f32_e32 v170, v170
	v_exp_f32_e32 v171, v171
	v_add_f32_e32 v3, 1.0, v3
	v_add_f32_e32 v5, 1.0, v5
	v_add_f32_e32 v151, 1.0, v151
	v_add_f32_e32 v153, 1.0, v153
	v_add_f32_e32 v155, 1.0, v155
	v_add_f32_e32 v161, 1.0, v161
	v_add_f32_e32 v179, 1.0, v170
	v_add_f32_e32 v181, 1.0, v171
	v_rcp_f32_e32 v170, v3
	v_rcp_f32_e32 v171, v5
	v_rcp_f32_e32 v172, v151
	v_rcp_f32_e32 v173, v153
	v_rcp_f32_e32 v178, v155
	v_rcp_f32_e32 v180, v179
	v_rcp_f32_e32 v181, v181
	v_rcp_f32_e32 v179, v161
	v_pk_mul_f32 v[172:173], v[108:109], v[172:173]
	v_pk_mul_f32 v[170:171], v[106:107], v[170:171]
	v_pk_mul_f32 v[180:181], v[104:105], v[180:181]
	v_pk_mul_f32 v[178:179], v[102:103], v[178:179]
	v_cvt_pk_bf16_f32 v170, v170, v171
	v_cvt_pk_bf16_f32 v171, v172, v173
	s_nop 0
	v_cvt_pk_bf16_f32 v172, v178, v179
	v_cvt_pk_bf16_f32 v173, v180, v181
	global_store_dwordx4 v[176:177], v[170:173], off
	global_load_dwordx4 v[170:173], v[174:175], off
	v_add_u32_e32 v174, 0x80, v4
	v_mad_i64_i32 v[178:179], s[38:39], v174, s73, v[166:167]
	v_lshl_add_u64 v[178:179], v[178:179], 0, s[14:15]
	v_lshl_add_u64 v[180:181], v[178:179], 0, v[156:157]
	s_waitcnt vmcnt(0)
	v_lshlrev_b32_e32 v3, 16, v170
	v_and_b32_e32 v5, 0xffff0000, v170
	v_lshlrev_b32_e32 v151, 16, v171
	v_and_b32_e32 v153, 0xffff0000, v171
	v_lshlrev_b32_e32 v155, 16, v172
	v_and_b32_e32 v161, 0xffff0000, v172
	v_lshlrev_b32_e32 v170, 16, v173
	v_and_b32_e32 v171, 0xffff0000, v173
	v_mul_f32_e32 v3, 0xbfb8aa3b, v3
	v_mul_f32_e32 v5, 0xbfb8aa3b, v5
	v_mul_f32_e32 v151, 0xbfb8aa3b, v151
	v_mul_f32_e32 v153, 0xbfb8aa3b, v153
	v_mul_f32_e32 v155, 0xbfb8aa3b, v155
	v_mul_f32_e32 v161, 0xbfb8aa3b, v161
	v_mul_f32_e32 v170, 0xbfb8aa3b, v170
	v_mul_f32_e32 v171, 0xbfb8aa3b, v171
	v_exp_f32_e32 v3, v3
	v_exp_f32_e32 v5, v5
	v_exp_f32_e32 v151, v151
	v_exp_f32_e32 v153, v153
	v_exp_f32_e32 v155, v155
	v_exp_f32_e32 v161, v161
	v_exp_f32_e32 v170, v170
	v_exp_f32_e32 v171, v171
	v_add_f32_e32 v3, 1.0, v3
	v_add_f32_e32 v5, 1.0, v5
	v_add_f32_e32 v151, 1.0, v151
	v_add_f32_e32 v153, 1.0, v153
	v_add_f32_e32 v155, 1.0, v155
	v_add_f32_e32 v161, 1.0, v161
	v_add_f32_e32 v175, 1.0, v170
	v_add_f32_e32 v183, 1.0, v171
	v_rcp_f32_e32 v170, v3
	v_rcp_f32_e32 v171, v5
	v_rcp_f32_e32 v172, v151
	v_rcp_f32_e32 v173, v153
	v_rcp_f32_e32 v182, v155
	v_rcp_f32_e32 v184, v175
	v_rcp_f32_e32 v185, v183
	v_rcp_f32_e32 v183, v161
	v_pk_mul_f32 v[172:173], v[76:77], v[172:173]
	v_pk_mul_f32 v[170:171], v[74:75], v[170:171]
	v_pk_mul_f32 v[184:185], v[72:73], v[184:185]
	v_pk_mul_f32 v[182:183], v[70:71], v[182:183]
	v_cvt_pk_bf16_f32 v170, v170, v171
	v_cvt_pk_bf16_f32 v171, v172, v173
	v_ashrrev_i32_e32 v175, 31, v174
	v_cvt_pk_bf16_f32 v172, v182, v183
	v_cvt_pk_bf16_f32 v173, v184, v185
	global_store_dwordx4 v[176:177], v[170:173], off offset:256
	global_load_dwordx4 v[170:173], v[180:181], off
	v_lshl_add_u64 v[176:177], v[178:179], 0, v[158:159]
	v_lshlrev_b64 v[174:175], 13, v[174:175]
	v_lshl_add_u64 v[174:175], s[28:29], 0, v[174:175]
	v_lshl_add_u64 v[174:175], v[174:175], 0, v[156:157]
	s_waitcnt vmcnt(0)
	v_lshlrev_b32_e32 v3, 16, v170
	v_and_b32_e32 v5, 0xffff0000, v170
	v_lshlrev_b32_e32 v151, 16, v171
	v_and_b32_e32 v153, 0xffff0000, v171
	v_lshlrev_b32_e32 v155, 16, v172
	v_and_b32_e32 v161, 0xffff0000, v172
	v_lshlrev_b32_e32 v170, 16, v173
	v_and_b32_e32 v171, 0xffff0000, v173
	v_mul_f32_e32 v3, 0xbfb8aa3b, v3
	v_mul_f32_e32 v5, 0xbfb8aa3b, v5
	v_mul_f32_e32 v151, 0xbfb8aa3b, v151
	v_mul_f32_e32 v153, 0xbfb8aa3b, v153
	v_mul_f32_e32 v155, 0xbfb8aa3b, v155
	v_mul_f32_e32 v161, 0xbfb8aa3b, v161
	v_mul_f32_e32 v170, 0xbfb8aa3b, v170
	v_mul_f32_e32 v171, 0xbfb8aa3b, v171
	v_exp_f32_e32 v3, v3
	v_exp_f32_e32 v5, v5
	v_exp_f32_e32 v151, v151
	v_exp_f32_e32 v153, v153
	v_exp_f32_e32 v155, v155
	v_exp_f32_e32 v161, v161
	v_exp_f32_e32 v170, v170
	v_exp_f32_e32 v171, v171
	v_add_f32_e32 v3, 1.0, v3
	v_add_f32_e32 v5, 1.0, v5
	v_add_f32_e32 v151, 1.0, v151
	v_add_f32_e32 v153, 1.0, v153
	v_add_f32_e32 v155, 1.0, v155
	v_add_f32_e32 v161, 1.0, v161
	v_add_f32_e32 v179, 1.0, v170
	v_add_f32_e32 v181, 1.0, v171
	v_rcp_f32_e32 v170, v3
	v_rcp_f32_e32 v171, v5
	v_rcp_f32_e32 v172, v151
	v_rcp_f32_e32 v173, v153
	v_rcp_f32_e32 v178, v155
	v_rcp_f32_e32 v180, v179
	v_rcp_f32_e32 v181, v181
	v_rcp_f32_e32 v179, v161
	v_pk_mul_f32 v[172:173], v[68:69], v[172:173]
	v_pk_mul_f32 v[170:171], v[66:67], v[170:171]
	v_pk_mul_f32 v[180:181], v[64:65], v[180:181]
	v_pk_mul_f32 v[178:179], v[62:63], v[178:179]
	v_cvt_pk_bf16_f32 v170, v170, v171
	v_cvt_pk_bf16_f32 v171, v172, v173
	s_nop 0
	v_cvt_pk_bf16_f32 v172, v178, v179
	v_cvt_pk_bf16_f32 v173, v180, v181
	global_store_dwordx4 v[174:175], v[170:173], off
	global_load_dwordx4 v[170:173], v[176:177], off
	v_add_u32_e32 v176, 0x90, v4
	v_mad_i64_i32 v[178:179], s[38:39], v176, s73, v[166:167]
	v_lshl_add_u64 v[178:179], v[178:179], 0, s[14:15]
	v_lshl_add_u64 v[180:181], v[178:179], 0, v[156:157]
	s_waitcnt vmcnt(0)
	v_lshlrev_b32_e32 v3, 16, v170
	v_and_b32_e32 v5, 0xffff0000, v170
	v_lshlrev_b32_e32 v151, 16, v171
	v_and_b32_e32 v153, 0xffff0000, v171
	v_lshlrev_b32_e32 v155, 16, v172
	v_and_b32_e32 v161, 0xffff0000, v172
	v_lshlrev_b32_e32 v170, 16, v173
	v_and_b32_e32 v171, 0xffff0000, v173
	v_mul_f32_e32 v3, 0xbfb8aa3b, v3
	v_mul_f32_e32 v5, 0xbfb8aa3b, v5
	v_mul_f32_e32 v151, 0xbfb8aa3b, v151
	v_mul_f32_e32 v153, 0xbfb8aa3b, v153
	v_mul_f32_e32 v155, 0xbfb8aa3b, v155
	v_mul_f32_e32 v161, 0xbfb8aa3b, v161
	v_mul_f32_e32 v170, 0xbfb8aa3b, v170
	v_mul_f32_e32 v171, 0xbfb8aa3b, v171
	v_exp_f32_e32 v3, v3
	v_exp_f32_e32 v5, v5
	v_exp_f32_e32 v151, v151
	v_exp_f32_e32 v153, v153
	v_exp_f32_e32 v155, v155
	v_exp_f32_e32 v161, v161
	v_exp_f32_e32 v170, v170
	v_exp_f32_e32 v171, v171
	v_add_f32_e32 v3, 1.0, v3
	v_add_f32_e32 v5, 1.0, v5
	v_add_f32_e32 v151, 1.0, v151
	v_add_f32_e32 v153, 1.0, v153
	v_add_f32_e32 v155, 1.0, v155
	v_add_f32_e32 v161, 1.0, v161
	v_add_f32_e32 v177, 1.0, v170
	v_add_f32_e32 v183, 1.0, v171
	v_rcp_f32_e32 v170, v3
	v_rcp_f32_e32 v171, v5
	v_rcp_f32_e32 v172, v151
	v_rcp_f32_e32 v173, v153
	v_rcp_f32_e32 v182, v155
	v_rcp_f32_e32 v184, v177
	v_rcp_f32_e32 v185, v183
	v_rcp_f32_e32 v183, v161
	v_pk_mul_f32 v[172:173], v[36:37], v[172:173]
	v_pk_mul_f32 v[170:171], v[34:35], v[170:171]
	v_pk_mul_f32 v[184:185], v[32:33], v[184:185]
	v_pk_mul_f32 v[182:183], v[30:31], v[182:183]
	v_cvt_pk_bf16_f32 v170, v170, v171
	v_cvt_pk_bf16_f32 v171, v172, v173
	v_ashrrev_i32_e32 v177, 31, v176
	v_cvt_pk_bf16_f32 v172, v182, v183
	v_cvt_pk_bf16_f32 v173, v184, v185
	global_store_dwordx4 v[174:175], v[170:173], off offset:256
	global_load_dwordx4 v[170:173], v[180:181], off
	v_lshlrev_b64 v[174:175], 13, v[176:177]
	v_lshl_add_u64 v[176:177], v[178:179], 0, v[158:159]
	v_lshl_add_u64 v[174:175], s[28:29], 0, v[174:175]
	v_lshl_add_u64 v[174:175], v[174:175], 0, v[156:157]
	s_waitcnt vmcnt(0)
	v_lshlrev_b32_e32 v3, 16, v170
	v_and_b32_e32 v5, 0xffff0000, v170
	v_lshlrev_b32_e32 v151, 16, v171
	v_and_b32_e32 v153, 0xffff0000, v171
	v_lshlrev_b32_e32 v155, 16, v172
	v_and_b32_e32 v161, 0xffff0000, v172
	v_lshlrev_b32_e32 v170, 16, v173
	v_and_b32_e32 v171, 0xffff0000, v173
	v_mul_f32_e32 v3, 0xbfb8aa3b, v3
	v_mul_f32_e32 v5, 0xbfb8aa3b, v5
	v_mul_f32_e32 v151, 0xbfb8aa3b, v151
	v_mul_f32_e32 v153, 0xbfb8aa3b, v153
	v_mul_f32_e32 v155, 0xbfb8aa3b, v155
	v_mul_f32_e32 v161, 0xbfb8aa3b, v161
	v_mul_f32_e32 v170, 0xbfb8aa3b, v170
	v_mul_f32_e32 v171, 0xbfb8aa3b, v171
	v_exp_f32_e32 v3, v3
	v_exp_f32_e32 v5, v5
	v_exp_f32_e32 v151, v151
	v_exp_f32_e32 v153, v153
	v_exp_f32_e32 v155, v155
	v_exp_f32_e32 v161, v161
	v_exp_f32_e32 v170, v170
	v_exp_f32_e32 v171, v171
	v_add_f32_e32 v3, 1.0, v3
	v_add_f32_e32 v5, 1.0, v5
	v_add_f32_e32 v151, 1.0, v151
	v_add_f32_e32 v153, 1.0, v153
	v_add_f32_e32 v155, 1.0, v155
	v_add_f32_e32 v161, 1.0, v161
	v_add_f32_e32 v179, 1.0, v170
	v_add_f32_e32 v181, 1.0, v171
	v_rcp_f32_e32 v170, v3
	v_rcp_f32_e32 v171, v5
	v_rcp_f32_e32 v172, v151
	v_rcp_f32_e32 v173, v153
	v_rcp_f32_e32 v178, v155
	v_rcp_f32_e32 v180, v179
	v_rcp_f32_e32 v181, v181
	v_rcp_f32_e32 v179, v161
	v_pk_mul_f32 v[172:173], v[60:61], v[172:173]
	v_pk_mul_f32 v[170:171], v[58:59], v[170:171]
	v_pk_mul_f32 v[180:181], v[56:57], v[180:181]
	v_pk_mul_f32 v[178:179], v[54:55], v[178:179]
	v_cvt_pk_bf16_f32 v170, v170, v171
	v_cvt_pk_bf16_f32 v171, v172, v173
	s_nop 0
	v_cvt_pk_bf16_f32 v172, v178, v179
	v_cvt_pk_bf16_f32 v173, v180, v181
	global_store_dwordx4 v[174:175], v[170:173], off
	global_load_dwordx4 v[170:173], v[176:177], off
	v_add_u32_e32 v176, 0xa0, v4
	v_mad_i64_i32 v[178:179], s[38:39], v176, s73, v[166:167]
	v_lshl_add_u64 v[178:179], v[178:179], 0, s[14:15]
	v_lshl_add_u64 v[180:181], v[178:179], 0, v[156:157]
	s_waitcnt vmcnt(0)
	v_lshlrev_b32_e32 v3, 16, v170
	v_and_b32_e32 v5, 0xffff0000, v170
	v_lshlrev_b32_e32 v151, 16, v171
	v_and_b32_e32 v153, 0xffff0000, v171
	v_lshlrev_b32_e32 v155, 16, v172
	v_and_b32_e32 v161, 0xffff0000, v172
	v_lshlrev_b32_e32 v170, 16, v173
	v_and_b32_e32 v171, 0xffff0000, v173
	v_mul_f32_e32 v3, 0xbfb8aa3b, v3
	v_mul_f32_e32 v5, 0xbfb8aa3b, v5
	v_mul_f32_e32 v151, 0xbfb8aa3b, v151
	v_mul_f32_e32 v153, 0xbfb8aa3b, v153
	v_mul_f32_e32 v155, 0xbfb8aa3b, v155
	v_mul_f32_e32 v161, 0xbfb8aa3b, v161
	v_mul_f32_e32 v170, 0xbfb8aa3b, v170
	v_mul_f32_e32 v171, 0xbfb8aa3b, v171
	v_exp_f32_e32 v3, v3
	v_exp_f32_e32 v5, v5
	v_exp_f32_e32 v151, v151
	v_exp_f32_e32 v153, v153
	v_exp_f32_e32 v155, v155
	v_exp_f32_e32 v161, v161
	v_exp_f32_e32 v170, v170
	v_exp_f32_e32 v171, v171
	v_add_f32_e32 v3, 1.0, v3
	v_add_f32_e32 v5, 1.0, v5
	v_add_f32_e32 v151, 1.0, v151
	v_add_f32_e32 v153, 1.0, v153
	v_add_f32_e32 v155, 1.0, v155
	v_add_f32_e32 v161, 1.0, v161
	v_add_f32_e32 v177, 1.0, v170
	v_add_f32_e32 v183, 1.0, v171
	v_rcp_f32_e32 v170, v3
	v_rcp_f32_e32 v171, v5
	v_rcp_f32_e32 v172, v151
	v_rcp_f32_e32 v173, v153
	v_rcp_f32_e32 v182, v155
	v_rcp_f32_e32 v184, v177
	v_rcp_f32_e32 v185, v183
	v_rcp_f32_e32 v183, v161
	v_pk_mul_f32 v[172:173], v[28:29], v[172:173]
	v_pk_mul_f32 v[170:171], v[26:27], v[170:171]
	v_pk_mul_f32 v[184:185], v[24:25], v[184:185]
	v_pk_mul_f32 v[182:183], v[22:23], v[182:183]
	v_cvt_pk_bf16_f32 v170, v170, v171
	v_cvt_pk_bf16_f32 v171, v172, v173
	v_ashrrev_i32_e32 v177, 31, v176
	v_cvt_pk_bf16_f32 v172, v182, v183
	v_cvt_pk_bf16_f32 v173, v184, v185
	global_store_dwordx4 v[174:175], v[170:173], off offset:256
	global_load_dwordx4 v[170:173], v[180:181], off
	v_lshlrev_b64 v[174:175], 13, v[176:177]
	v_lshl_add_u64 v[176:177], v[178:179], 0, v[158:159]
	v_lshl_add_u64 v[174:175], s[28:29], 0, v[174:175]
	v_lshl_add_u64 v[174:175], v[174:175], 0, v[156:157]
	s_waitcnt vmcnt(0)
	v_lshlrev_b32_e32 v3, 16, v170
	v_and_b32_e32 v5, 0xffff0000, v170
	v_lshlrev_b32_e32 v151, 16, v171
	v_and_b32_e32 v153, 0xffff0000, v171
	v_lshlrev_b32_e32 v155, 16, v172
	v_and_b32_e32 v161, 0xffff0000, v172
	v_lshlrev_b32_e32 v170, 16, v173
	v_and_b32_e32 v171, 0xffff0000, v173
	v_mul_f32_e32 v3, 0xbfb8aa3b, v3
	v_mul_f32_e32 v5, 0xbfb8aa3b, v5
	v_mul_f32_e32 v151, 0xbfb8aa3b, v151
	v_mul_f32_e32 v153, 0xbfb8aa3b, v153
	v_mul_f32_e32 v155, 0xbfb8aa3b, v155
	v_mul_f32_e32 v161, 0xbfb8aa3b, v161
	v_mul_f32_e32 v170, 0xbfb8aa3b, v170
	v_mul_f32_e32 v171, 0xbfb8aa3b, v171
	v_exp_f32_e32 v3, v3
	v_exp_f32_e32 v5, v5
	v_exp_f32_e32 v151, v151
	v_exp_f32_e32 v153, v153
	v_exp_f32_e32 v155, v155
	v_exp_f32_e32 v161, v161
	v_exp_f32_e32 v170, v170
	v_exp_f32_e32 v171, v171
	v_add_f32_e32 v3, 1.0, v3
	v_add_f32_e32 v5, 1.0, v5
	v_add_f32_e32 v151, 1.0, v151
	v_add_f32_e32 v153, 1.0, v153
	v_add_f32_e32 v155, 1.0, v155
	v_add_f32_e32 v161, 1.0, v161
	v_add_f32_e32 v179, 1.0, v170
	v_add_f32_e32 v181, 1.0, v171
	v_rcp_f32_e32 v170, v3
	v_rcp_f32_e32 v171, v5
	v_rcp_f32_e32 v172, v151
	v_rcp_f32_e32 v173, v153
	v_rcp_f32_e32 v178, v155
	v_rcp_f32_e32 v180, v179
	v_rcp_f32_e32 v181, v181
	v_rcp_f32_e32 v179, v161
	v_pk_mul_f32 v[172:173], v[52:53], v[172:173]
	v_pk_mul_f32 v[170:171], v[50:51], v[170:171]
	v_pk_mul_f32 v[180:181], v[48:49], v[180:181]
	v_pk_mul_f32 v[178:179], v[46:47], v[178:179]
	v_cvt_pk_bf16_f32 v170, v170, v171
	v_cvt_pk_bf16_f32 v171, v172, v173
	s_nop 0
	v_cvt_pk_bf16_f32 v172, v178, v179
	v_cvt_pk_bf16_f32 v173, v180, v181
	global_store_dwordx4 v[174:175], v[170:173], off
	global_load_dwordx4 v[170:173], v[176:177], off
	v_add_u32_e32 v176, 0xb0, v4
	v_mad_i64_i32 v[166:167], s[38:39], v176, s73, v[166:167]
	v_lshl_add_u64 v[166:167], v[166:167], 0, s[14:15]
	v_lshl_add_u64 v[178:179], v[166:167], 0, v[156:157]
	v_lshl_add_u64 v[166:167], v[166:167], 0, v[158:159]
	s_waitcnt vmcnt(0)
	v_lshlrev_b32_e32 v3, 16, v170
	v_and_b32_e32 v5, 0xffff0000, v170
	v_lshlrev_b32_e32 v151, 16, v171
	v_and_b32_e32 v153, 0xffff0000, v171
	v_lshlrev_b32_e32 v155, 16, v172
	v_and_b32_e32 v161, 0xffff0000, v172
	v_lshlrev_b32_e32 v170, 16, v173
	v_and_b32_e32 v171, 0xffff0000, v173
	v_mul_f32_e32 v3, 0xbfb8aa3b, v3
	v_mul_f32_e32 v5, 0xbfb8aa3b, v5
	v_mul_f32_e32 v151, 0xbfb8aa3b, v151
	v_mul_f32_e32 v153, 0xbfb8aa3b, v153
	v_mul_f32_e32 v155, 0xbfb8aa3b, v155
	v_mul_f32_e32 v161, 0xbfb8aa3b, v161
	v_mul_f32_e32 v170, 0xbfb8aa3b, v170
	v_mul_f32_e32 v171, 0xbfb8aa3b, v171
	v_exp_f32_e32 v3, v3
	v_exp_f32_e32 v5, v5
	v_exp_f32_e32 v151, v151
	v_exp_f32_e32 v153, v153
	v_exp_f32_e32 v155, v155
	v_exp_f32_e32 v161, v161
	v_exp_f32_e32 v170, v170
	v_exp_f32_e32 v171, v171
	v_add_f32_e32 v3, 1.0, v3
	v_add_f32_e32 v5, 1.0, v5
	v_add_f32_e32 v151, 1.0, v151
	v_add_f32_e32 v153, 1.0, v153
	v_add_f32_e32 v155, 1.0, v155
	v_add_f32_e32 v161, 1.0, v161
	v_add_f32_e32 v177, 1.0, v170
	v_add_f32_e32 v181, 1.0, v171
	v_rcp_f32_e32 v170, v3
	v_rcp_f32_e32 v171, v5
	v_rcp_f32_e32 v172, v151
	v_rcp_f32_e32 v173, v153
	v_rcp_f32_e32 v180, v155
	v_rcp_f32_e32 v182, v177
	v_rcp_f32_e32 v183, v181
	v_rcp_f32_e32 v181, v161
	v_pk_mul_f32 v[172:173], v[20:21], v[172:173]
	v_pk_mul_f32 v[170:171], v[18:19], v[170:171]
	v_pk_mul_f32 v[182:183], v[16:17], v[182:183]
	v_pk_mul_f32 v[180:181], v[14:15], v[180:181]
	v_cvt_pk_bf16_f32 v170, v170, v171
	v_cvt_pk_bf16_f32 v171, v172, v173
	v_ashrrev_i32_e32 v177, 31, v176
	v_cvt_pk_bf16_f32 v172, v180, v181
	v_cvt_pk_bf16_f32 v173, v182, v183
	global_store_dwordx4 v[174:175], v[170:173], off offset:256
	global_load_dwordx4 v[170:173], v[178:179], off
	v_lshlrev_b64 v[174:175], 13, v[176:177]
	v_lshl_add_u64 v[174:175], s[28:29], 0, v[174:175]
	v_lshl_add_u64 v[174:175], v[174:175], 0, v[156:157]
	s_waitcnt vmcnt(0)
	v_lshlrev_b32_e32 v3, 16, v170
	v_and_b32_e32 v5, 0xffff0000, v170
	v_lshlrev_b32_e32 v151, 16, v171
	v_and_b32_e32 v153, 0xffff0000, v171
	v_lshlrev_b32_e32 v155, 16, v172
	v_and_b32_e32 v156, 0xffff0000, v172
	v_lshlrev_b32_e32 v157, 16, v173
	v_and_b32_e32 v158, 0xffff0000, v173
	v_mul_f32_e32 v3, 0xbfb8aa3b, v3
	v_mul_f32_e32 v5, 0xbfb8aa3b, v5
	v_mul_f32_e32 v151, 0xbfb8aa3b, v151
	v_mul_f32_e32 v153, 0xbfb8aa3b, v153
	v_mul_f32_e32 v155, 0xbfb8aa3b, v155
	v_mul_f32_e32 v156, 0xbfb8aa3b, v156
	v_mul_f32_e32 v157, 0xbfb8aa3b, v157
	v_mul_f32_e32 v158, 0xbfb8aa3b, v158
	v_exp_f32_e32 v3, v3
	v_exp_f32_e32 v5, v5
	v_exp_f32_e32 v151, v151
	v_exp_f32_e32 v153, v153
	v_exp_f32_e32 v155, v155
	v_exp_f32_e32 v156, v156
	v_exp_f32_e32 v157, v157
	v_exp_f32_e32 v158, v158
	v_add_f32_e32 v3, 1.0, v3
	v_add_f32_e32 v5, 1.0, v5
	v_add_f32_e32 v151, 1.0, v151
	v_add_f32_e32 v153, 1.0, v153
	v_add_f32_e32 v155, 1.0, v155
	v_add_f32_e32 v161, 1.0, v156
	v_add_f32_e32 v171, 1.0, v157
	v_add_f32_e32 v173, 1.0, v158
	v_rcp_f32_e32 v156, v3
	v_rcp_f32_e32 v157, v5
	v_rcp_f32_e32 v158, v151
	v_rcp_f32_e32 v159, v153
	v_rcp_f32_e32 v170, v155
	v_rcp_f32_e32 v172, v171
	v_rcp_f32_e32 v173, v173
	v_rcp_f32_e32 v171, v161
	v_pk_mul_f32 v[158:159], v[44:45], v[158:159]
	v_pk_mul_f32 v[156:157], v[42:43], v[156:157]
	v_pk_mul_f32 v[172:173], v[40:41], v[172:173]
	v_pk_mul_f32 v[170:171], v[38:39], v[170:171]
	v_cvt_pk_bf16_f32 v156, v156, v157
	v_cvt_pk_bf16_f32 v157, v158, v159
	s_nop 0
	v_cvt_pk_bf16_f32 v158, v170, v171
	v_cvt_pk_bf16_f32 v159, v172, v173
	global_store_dwordx4 v[174:175], v[156:159], off
	global_load_dwordx4 v[156:159], v[166:167], off
	s_waitcnt vmcnt(0)
	v_lshlrev_b32_e32 v3, 16, v156
	v_and_b32_e32 v5, 0xffff0000, v156
	v_lshlrev_b32_e32 v151, 16, v157
	v_and_b32_e32 v153, 0xffff0000, v157
	v_lshlrev_b32_e32 v155, 16, v158
	v_and_b32_e32 v156, 0xffff0000, v158
	v_lshlrev_b32_e32 v157, 16, v159
	v_and_b32_e32 v158, 0xffff0000, v159
	v_mul_f32_e32 v3, 0xbfb8aa3b, v3
	v_mul_f32_e32 v5, 0xbfb8aa3b, v5
	v_mul_f32_e32 v151, 0xbfb8aa3b, v151
	v_mul_f32_e32 v153, 0xbfb8aa3b, v153
	v_mul_f32_e32 v155, 0xbfb8aa3b, v155
	v_mul_f32_e32 v156, 0xbfb8aa3b, v156
	v_mul_f32_e32 v157, 0xbfb8aa3b, v157
	v_mul_f32_e32 v158, 0xbfb8aa3b, v158
	v_exp_f32_e32 v3, v3
	v_exp_f32_e32 v5, v5
	v_exp_f32_e32 v151, v151
	v_exp_f32_e32 v153, v153
	v_exp_f32_e32 v155, v155
	v_exp_f32_e32 v156, v156
	v_exp_f32_e32 v157, v157
	v_exp_f32_e32 v158, v158
	v_add_f32_e32 v3, 1.0, v3
	v_add_f32_e32 v5, 1.0, v5
	v_add_f32_e32 v151, 1.0, v151
	v_add_f32_e32 v153, 1.0, v153
	v_add_f32_e32 v155, 1.0, v155
	v_add_f32_e32 v161, 1.0, v156
	v_add_f32_e32 v167, 1.0, v157
	v_add_f32_e32 v171, 1.0, v158
	v_rcp_f32_e32 v156, v3
	v_rcp_f32_e32 v157, v5
	v_rcp_f32_e32 v158, v151
	v_rcp_f32_e32 v159, v153
	v_rcp_f32_e32 v166, v155
	v_rcp_f32_e32 v170, v167
	v_rcp_f32_e32 v171, v171
	v_rcp_f32_e32 v167, v161
	v_pk_mul_f32 v[158:159], v[12:13], v[158:159]
	v_pk_mul_f32 v[156:157], v[10:11], v[156:157]
	v_pk_mul_f32 v[170:171], v[8:9], v[170:171]
	v_pk_mul_f32 v[166:167], v[6:7], v[166:167]
	v_cvt_pk_bf16_f32 v156, v156, v157
	v_cvt_pk_bf16_f32 v157, v158, v159
	s_nop 0
	v_cvt_pk_bf16_f32 v158, v166, v167
	v_cvt_pk_bf16_f32 v159, v170, v171
	global_store_dwordx4 v[174:175], v[156:159], off offset:256
	s_cbranch_execnz .LBB0_1232
.LBB0_1231:
	s_nop 0
	v_mov_b64_e32 v[158:159], s[46:47]
	v_mad_i64_i32 v[166:167], s[38:39], v4, s73, v[158:159]
	v_ashrrev_i32_e32 v155, 31, v154
	v_lshl_add_u64 v[178:179], v[166:167], 0, s[16:17]
	v_lshlrev_b64 v[156:157], 1, v[154:155]
	v_or_b32_e32 v154, 0x80, v154
	v_lshl_add_u64 v[170:171], v[178:179], 0, v[156:157]
	v_lshl_add_u64 v[166:167], v[166:167], 0, s[14:15]
	v_ashrrev_i32_e32 v155, 31, v154
	global_load_dwordx4 v[170:173], v[170:171], off
	v_lshl_add_u64 v[174:175], v[166:167], 0, v[156:157]
	v_lshlrev_b64 v[154:155], 1, v[154:155]
	global_load_dwordx4 v[174:177], v[174:175], off
	v_lshl_add_u64 v[178:179], v[178:179], 0, v[154:155]
	global_load_dwordx4 v[178:181], v[178:179], off
	v_lshl_add_u64 v[166:167], v[166:167], 0, v[154:155]
	global_load_dwordx4 v[182:185], v[166:167], off
	s_mov_b32 s76, 0xa4000
	s_mov_b32 s77, 0
	s_mov_b32 s78, 0x334000
	s_mov_b32 s79, 0
	s_sub_u32 s80, s16, s14
	s_subb_u32 s81, s17, s15
	v_mov_b64_e32 v[204:205], v[166:167]
	v_lshl_add_u64 v[204:205], v[204:205], 0, s[76:77]
	v_lshl_add_u64 v[206:207], v[204:205], 0, s[80:81]
	global_load_dword v202, v[204:205], off
	global_load_dword v202, v[204:205], off offset:-256
	global_load_dword v202, v[206:207], off
	global_load_dword v202, v[206:207], off offset:-256
	v_lshl_add_u64 v[204:205], v[204:205], 0, s[76:77]
	v_lshl_add_u64 v[206:207], v[204:205], 0, s[80:81]
	global_load_dword v202, v[204:205], off
	global_load_dword v202, v[204:205], off offset:-256
	global_load_dword v202, v[206:207], off
	global_load_dword v202, v[206:207], off offset:-256
	v_lshl_add_u64 v[204:205], v[204:205], 0, s[76:77]
	v_lshl_add_u64 v[206:207], v[204:205], 0, s[80:81]
	global_load_dword v202, v[204:205], off
	global_load_dword v202, v[204:205], off offset:-256
	global_load_dword v202, v[206:207], off
	global_load_dword v202, v[206:207], off offset:-256
	v_lshl_add_u64 v[204:205], v[204:205], 0, s[78:79]
	v_lshl_add_u64 v[206:207], v[204:205], 0, s[80:81]
	global_load_dword v202, v[204:205], off
	global_load_dword v202, v[204:205], off offset:-256
	global_load_dword v202, v[206:207], off
	global_load_dword v202, v[206:207], off offset:-256
	v_lshl_add_u64 v[204:205], v[204:205], 0, s[76:77]
	v_lshl_add_u64 v[206:207], v[204:205], 0, s[80:81]
	global_load_dword v202, v[204:205], off
	global_load_dword v202, v[204:205], off offset:-256
	global_load_dword v202, v[206:207], off
	global_load_dword v202, v[206:207], off offset:-256
	v_lshl_add_u64 v[204:205], v[204:205], 0, s[76:77]
	v_lshl_add_u64 v[206:207], v[204:205], 0, s[80:81]
	global_load_dword v202, v[204:205], off
	global_load_dword v202, v[204:205], off offset:-256
	global_load_dword v202, v[206:207], off
	global_load_dword v202, v[206:207], off offset:-256
	v_lshl_add_u64 v[204:205], v[204:205], 0, s[76:77]
	v_lshl_add_u64 v[206:207], v[204:205], 0, s[80:81]
	global_load_dword v202, v[204:205], off
	global_load_dword v202, v[204:205], off offset:-256
	global_load_dword v202, v[206:207], off
	global_load_dword v202, v[206:207], off offset:-256
	s_waitcnt vmcnt(0)
	v_lshlrev_b32_e32 v3, 16, v170
	v_and_b32_e32 v5, 0xffff0000, v170
	v_lshlrev_b32_e32 v151, 16, v171
	v_and_b32_e32 v153, 0xffff0000, v171
	v_lshlrev_b32_e32 v161, 16, v172
	v_and_b32_e32 v166, 0xffff0000, v172
	v_lshlrev_b32_e32 v167, 16, v173
	v_and_b32_e32 v170, 0xffff0000, v173
	v_lshlrev_b32_e32 v171, 16, v174
	v_and_b32_e32 v172, 0xffff0000, v174
	v_lshlrev_b32_e32 v173, 16, v175
	v_and_b32_e32 v174, 0xffff0000, v175
	v_lshlrev_b32_e32 v175, 16, v176
	v_and_b32_e32 v176, 0xffff0000, v176
	v_lshlrev_b32_e32 v186, 16, v177
	v_and_b32_e32 v177, 0xffff0000, v177
	v_mul_f32_e32 v3, 0xbfb8aa3b, v3
	v_mul_f32_e32 v5, 0xbfb8aa3b, v5
	v_lshlrev_b32_e32 v192, 16, v178
	v_and_b32_e32 v193, 0xffff0000, v178
	v_mul_f32_e32 v171, 0xbfb8aa3b, v171
	v_mul_f32_e32 v175, 0xbfb8aa3b, v175
	v_mul_f32_e32 v161, 0xbfb8aa3b, v161
	v_mul_f32_e32 v176, 0xbfb8aa3b, v176
	v_mul_f32_e32 v178, 0xbfb8aa3b, v166
	v_mul_f32_e32 v177, 0xbfb8aa3b, v177
	v_mul_f32_e32 v189, 0xbfb8aa3b, v170
	v_exp_f32_e32 v3, v3
	v_exp_f32_e32 v5, v5
	v_mul_f32_e32 v151, 0xbfb8aa3b, v151
	v_mul_f32_e32 v153, 0xbfb8aa3b, v153
	v_exp_f32_e32 v166, v171
	v_exp_f32_e32 v170, v175
	v_exp_f32_e32 v161, v161
	v_exp_f32_e32 v171, v176
	v_exp_f32_e32 v176, v178
	v_exp_f32_e32 v175, v177
	v_exp_f32_e32 v177, v189
	v_exp_f32_e32 v151, v151
	v_exp_f32_e32 v153, v153
	v_mul_f32_e32 v172, 0xbfb8aa3b, v172
	v_mul_f32_e32 v187, 0xbfb8aa3b, v167
	v_exp_f32_e32 v167, v172
	v_add_f32_e32 v3, 1.0, v3
	v_add_f32_e32 v5, 1.0, v5
	v_mul_f32_e32 v173, 0xbfb8aa3b, v173
	v_mul_f32_e32 v186, 0xbfb8aa3b, v186
	v_mul_f32_e32 v188, 0xbfb8aa3b, v174
	v_exp_f32_e32 v178, v187
	v_add_f32_e32 v161, 1.0, v161
	v_add_f32_e32 v187, 1.0, v176
	v_add_f32_e32 v191, 1.0, v177
	v_rcp_f32_e32 v176, v3
	v_rcp_f32_e32 v177, v5
	v_exp_f32_e32 v172, v173
	v_exp_f32_e32 v174, v186
	v_exp_f32_e32 v173, v188
	v_add_f32_e32 v151, 1.0, v151
	v_add_f32_e32 v153, 1.0, v153
	v_rcp_f32_e32 v186, v161
	v_rcp_f32_e32 v187, v187
	v_rcp_f32_e32 v188, v151
	v_rcp_f32_e32 v189, v153
	v_pk_add_f32 v[166:167], v[166:167], 1.0 op_sel_hi:[1,0]
	v_pk_add_f32 v[170:171], v[170:171], 1.0 op_sel_hi:[1,0]
	v_pk_mul_f32 v[166:167], v[166:167], v[176:177]
	v_mad_i64_i32 v[160:161], s[38:39], v160, s73, v[158:159]
	v_pk_add_f32 v[172:173], v[172:173], 1.0 op_sel_hi:[1,0]
	v_pk_mul_f32 v[170:171], v[170:171], v[186:187]
	v_pk_mul_f32 v[130:131], v[130:131], v[166:167]
	v_lshl_add_u64 v[166:167], v[160:161], 0, s[16:17]
	v_add_f32_e32 v178, 1.0, v178
	v_pk_mul_f32 v[172:173], v[172:173], v[188:189]
	v_pk_mul_f32 v[126:127], v[126:127], v[170:171]
	v_lshl_add_u64 v[170:171], v[166:167], 0, v[156:157]
	v_rcp_f32_e32 v190, v178
	v_rcp_f32_e32 v191, v191
	v_pk_mul_f32 v[132:133], v[132:133], v[172:173]
	global_load_dwordx4 v[170:173], v[170:171], off
	v_pk_add_f32 v[174:175], v[174:175], 1.0 op_sel_hi:[1,0]
	v_lshl_add_u64 v[160:161], v[160:161], 0, s[14:15]
	v_pk_mul_f32 v[174:175], v[174:175], v[190:191]
	v_lshlrev_b32_e32 v151, 16, v180
	v_pk_mul_f32 v[128:129], v[128:129], v[174:175]
	v_lshl_add_u64 v[174:175], v[160:161], 0, v[156:157]
	global_load_dwordx4 v[174:177], v[174:175], off
	v_lshlrev_b32_e32 v187, 16, v181
	v_and_b32_e32 v191, 0xffff0000, v181
	v_lshlrev_b32_e32 v181, 16, v184
	v_mul_f32_e32 v151, 0xbfb8aa3b, v151
	v_exp_f32_e32 v151, v151
	v_mul_f32_e32 v181, 0xbfb8aa3b, v181
	v_lshlrev_b32_e32 v3, 16, v179
	v_and_b32_e32 v5, 0xffff0000, v179
	v_lshlrev_b32_e32 v178, 16, v182
	v_and_b32_e32 v179, 0xffff0000, v182
	v_exp_f32_e32 v182, v181
	v_mul_f32_e32 v181, 0xbfb8aa3b, v193
	v_and_b32_e32 v153, 0xffff0000, v180
	v_exp_f32_e32 v181, v181
	v_mul_f32_e32 v153, 0xbfb8aa3b, v153
	v_add_f32_e32 v151, 1.0, v151
	v_exp_f32_e32 v153, v153
	v_lshlrev_b32_e32 v186, 16, v183
	v_and_b32_e32 v189, 0xffff0000, v183
	v_and_b32_e32 v183, 0xffff0000, v184
	v_rcp_f32_e32 v184, v151
	v_mul_f32_e32 v151, 0xbfb8aa3b, v179
	v_exp_f32_e32 v179, v151
	v_add_f32_e32 v151, 1.0, v181
	v_rcp_f32_e32 v181, v151
	v_mul_f32_e32 v151, 0xbfb8aa3b, v183
	v_exp_f32_e32 v183, v151
	v_add_f32_e32 v151, 1.0, v153
	v_mul_f32_e32 v3, 0xbfb8aa3b, v3
	v_lshlrev_b32_e32 v190, 16, v185
	v_and_b32_e32 v194, 0xffff0000, v185
	v_exp_f32_e32 v3, v3
	v_rcp_f32_e32 v185, v151
	v_mul_f32_e32 v151, 0xbfb8aa3b, v186
	v_exp_f32_e32 v186, v151
	v_mul_f32_e32 v151, 0xbfb8aa3b, v187
	v_exp_f32_e32 v151, v151
	v_mul_f32_e32 v5, 0xbfb8aa3b, v5
	v_exp_f32_e32 v5, v5
	v_add_f32_e32 v3, 1.0, v3
	v_rcp_f32_e32 v188, v3
	v_mul_f32_e32 v3, 0xbfb8aa3b, v190
	v_mul_f32_e32 v180, 0xbfb8aa3b, v192
	v_exp_f32_e32 v190, v3
	v_add_f32_e32 v3, 1.0, v151
	v_exp_f32_e32 v180, v180
	v_rcp_f32_e32 v192, v3
	v_add_f32_e32 v3, 1.0, v5
	v_mul_f32_e32 v151, 0xbfb8aa3b, v189
	v_rcp_f32_e32 v189, v3
	v_mul_f32_e32 v3, 0xbfb8aa3b, v191
	v_exp_f32_e32 v3, v3
	v_mul_f32_e32 v178, 0xbfb8aa3b, v178
	v_exp_f32_e32 v178, v178
	v_add_f32_e32 v180, 1.0, v180
	v_rcp_f32_e32 v180, v180
	v_exp_f32_e32 v187, v151
	v_mul_f32_e32 v5, 0xbfb8aa3b, v194
	v_exp_f32_e32 v191, v5
	v_add_f32_e32 v3, 1.0, v3
	v_rcp_f32_e32 v193, v3
	v_pk_add_f32 v[178:179], v[178:179], 1.0 op_sel_hi:[1,0]
	v_pk_add_f32 v[186:187], v[186:187], 1.0 op_sel_hi:[1,0]
	v_pk_mul_f32 v[178:179], v[178:179], v[180:181]
	v_pk_mul_f32 v[180:181], v[186:187], v[188:189]
	v_pk_mul_f32 v[98:99], v[98:99], v[178:179]
	v_pk_add_f32 v[178:179], v[190:191], 1.0 op_sel_hi:[1,0]
	v_pk_mul_f32 v[100:101], v[100:101], v[180:181]
	v_pk_add_f32 v[180:181], v[182:183], 1.0 op_sel_hi:[1,0]
	v_pk_mul_f32 v[178:179], v[178:179], v[192:193]
	v_lshl_add_u64 v[166:167], v[166:167], 0, v[154:155]
	v_pk_mul_f32 v[182:183], v[180:181], v[184:185]
	v_pk_mul_f32 v[96:97], v[96:97], v[178:179]
	global_load_dwordx4 v[178:181], v[166:167], off
	s_waitcnt vmcnt(2)
	v_lshlrev_b32_e32 v3, 16, v170
	v_mul_f32_e32 v3, 0xbfb8aa3b, v3
	v_lshlrev_b32_e32 v166, 16, v172
	v_lshl_add_u64 v[160:161], v[160:161], 0, v[154:155]
	v_exp_f32_e32 v3, v3
	v_pk_mul_f32 v[94:95], v[94:95], v[182:183]
	v_and_b32_e32 v5, 0xffff0000, v170
	v_lshlrev_b32_e32 v151, 16, v171
	v_and_b32_e32 v153, 0xffff0000, v171
	v_and_b32_e32 v167, 0xffff0000, v172
	v_lshlrev_b32_e32 v183, 16, v173
	v_and_b32_e32 v187, 0xffff0000, v173
	global_load_dwordx4 v[170:173], v[160:161], off
	v_mul_f32_e32 v161, 0xbfb8aa3b, v166
	v_exp_f32_e32 v161, v161
	v_mul_f32_e32 v5, 0xbfb8aa3b, v5
	s_waitcnt vmcnt(2)
	v_lshlrev_b32_e32 v182, 16, v174
	v_and_b32_e32 v184, 0xffff0000, v174
	v_lshlrev_b32_e32 v174, 16, v176
	v_add_f32_e32 v3, 1.0, v3
	v_exp_f32_e32 v5, v5
	v_rcp_f32_e32 v166, v3
	v_mul_f32_e32 v3, 0xbfb8aa3b, v174
	v_exp_f32_e32 v174, v3
	v_add_f32_e32 v3, 1.0, v161
	v_lshlrev_b32_e32 v185, 16, v175
	v_and_b32_e32 v188, 0xffff0000, v175
	v_and_b32_e32 v175, 0xffff0000, v176
	v_rcp_f32_e32 v176, v3
	v_mul_f32_e32 v3, 0xbfb8aa3b, v184
	v_exp_f32_e32 v161, v3
	v_add_f32_e32 v3, 1.0, v5
	v_mul_f32_e32 v5, 0xbfb8aa3b, v167
	v_exp_f32_e32 v5, v5
	v_rcp_f32_e32 v167, v3
	v_mul_f32_e32 v3, 0xbfb8aa3b, v175
	v_exp_f32_e32 v175, v3
	v_add_f32_e32 v3, 1.0, v5
	v_mul_f32_e32 v5, 0xbfb8aa3b, v151
	v_exp_f32_e32 v5, v5
	v_lshlrev_b32_e32 v186, 16, v177
	v_and_b32_e32 v189, 0xffff0000, v177
	v_rcp_f32_e32 v177, v3
	v_mul_f32_e32 v3, 0xbfb8aa3b, v185
	v_mul_f32_e32 v160, 0xbfb8aa3b, v182
	v_exp_f32_e32 v182, v3
	v_add_f32_e32 v3, 1.0, v5
	v_mul_f32_e32 v5, 0xbfb8aa3b, v183
	v_exp_f32_e32 v5, v5
	v_rcp_f32_e32 v184, v3
	v_mul_f32_e32 v3, 0xbfb8aa3b, v186
	v_exp_f32_e32 v186, v3
	v_add_f32_e32 v3, 1.0, v5
	v_mul_f32_e32 v5, 0xbfb8aa3b, v153
	v_exp_f32_e32 v5, v5
	v_mul_f32_e32 v151, 0xbfb8aa3b, v188
	v_rcp_f32_e32 v188, v3
	v_exp_f32_e32 v160, v160
	v_add_f32_e32 v3, 1.0, v5
	v_rcp_f32_e32 v185, v3
	v_mul_f32_e32 v3, 0xbfb8aa3b, v187
	v_exp_f32_e32 v3, v3
	v_exp_f32_e32 v183, v151
	v_mul_f32_e32 v5, 0xbfb8aa3b, v189
	v_exp_f32_e32 v187, v5
	v_add_f32_e32 v3, 1.0, v3
	v_rcp_f32_e32 v189, v3
	v_pk_add_f32 v[160:161], v[160:161], 1.0 op_sel_hi:[1,0]
	v_pk_add_f32 v[182:183], v[182:183], 1.0 op_sel_hi:[1,0]
	v_pk_mul_f32 v[160:161], v[160:161], v[166:167]
	v_pk_mul_f32 v[166:167], v[182:183], v[184:185]
	v_pk_mul_f32 v[122:123], v[122:123], v[160:161]
	v_pk_add_f32 v[160:161], v[186:187], 1.0 op_sel_hi:[1,0]
	v_pk_mul_f32 v[124:125], v[124:125], v[166:167]
	v_pk_add_f32 v[166:167], v[174:175], 1.0 op_sel_hi:[1,0]
	v_pk_mul_f32 v[160:161], v[160:161], v[188:189]
	v_mad_i64_i32 v[152:153], s[38:39], v152, s73, v[158:159]
	v_pk_mul_f32 v[166:167], v[166:167], v[176:177]
	v_pk_mul_f32 v[120:121], v[120:121], v[160:161]
	v_lshl_add_u64 v[160:161], v[152:153], 0, s[16:17]
	v_pk_mul_f32 v[118:119], v[118:119], v[166:167]
	v_lshl_add_u64 v[166:167], v[160:161], 0, v[156:157]
	global_load_dwordx4 v[174:177], v[166:167], off
	v_lshl_add_u64 v[152:153], v[152:153], 0, s[14:15]
	v_lshl_add_u64 v[166:167], v[152:153], 0, v[156:157]
	global_load_dwordx4 v[182:185], v[166:167], off
	s_waitcnt vmcnt(3)
	v_lshlrev_b32_e32 v3, 16, v178
	v_mul_f32_e32 v3, 0xbfb8aa3b, v3
	v_and_b32_e32 v5, 0xffff0000, v178
	v_lshlrev_b32_e32 v178, 16, v180
	v_exp_f32_e32 v3, v3
	s_waitcnt vmcnt(2)
	v_lshlrev_b32_e32 v166, 16, v170
	v_and_b32_e32 v167, 0xffff0000, v170
	v_mul_f32_e32 v170, 0xbfb8aa3b, v178
	v_lshlrev_b32_e32 v190, 16, v173
	v_and_b32_e32 v191, 0xffff0000, v173
	v_exp_f32_e32 v173, v170
	v_mul_f32_e32 v5, 0xbfb8aa3b, v5
	v_lshlrev_b32_e32 v151, 16, v179
	v_and_b32_e32 v187, 0xffff0000, v179
	v_and_b32_e32 v179, 0xffff0000, v180
	v_lshlrev_b32_e32 v186, 16, v181
	v_and_b32_e32 v189, 0xffff0000, v181
	v_lshlrev_b32_e32 v180, 16, v171
	v_and_b32_e32 v181, 0xffff0000, v171
	v_lshlrev_b32_e32 v171, 16, v172
	v_add_f32_e32 v3, 1.0, v3
	v_exp_f32_e32 v5, v5
	v_rcp_f32_e32 v170, v3
	v_mul_f32_e32 v3, 0xbfb8aa3b, v171
	v_and_b32_e32 v188, 0xffff0000, v172
	v_exp_f32_e32 v172, v3
	v_add_f32_e32 v3, 1.0, v173
	v_rcp_f32_e32 v178, v3
	v_mul_f32_e32 v3, 0xbfb8aa3b, v167
	v_exp_f32_e32 v167, v3
	v_add_f32_e32 v3, 1.0, v5
	v_mul_f32_e32 v5, 0xbfb8aa3b, v179
	v_exp_f32_e32 v5, v5
	v_rcp_f32_e32 v171, v3
	v_mul_f32_e32 v3, 0xbfb8aa3b, v188
	v_exp_f32_e32 v173, v3
	v_add_f32_e32 v3, 1.0, v5
	v_mul_f32_e32 v5, 0xbfb8aa3b, v151
	v_exp_f32_e32 v5, v5
	v_rcp_f32_e32 v179, v3
	v_mul_f32_e32 v3, 0xbfb8aa3b, v180
	v_exp_f32_e32 v180, v3
	v_add_f32_e32 v3, 1.0, v5
	v_mul_f32_e32 v5, 0xbfb8aa3b, v186
	v_exp_f32_e32 v5, v5
	v_rcp_f32_e32 v186, v3
	v_mul_f32_e32 v3, 0xbfb8aa3b, v190
	v_exp_f32_e32 v188, v3
	v_add_f32_e32 v3, 1.0, v5
	v_mul_f32_e32 v5, 0xbfb8aa3b, v187
	v_exp_f32_e32 v5, v5
	v_mul_f32_e32 v166, 0xbfb8aa3b, v166
	v_mul_f32_e32 v151, 0xbfb8aa3b, v181
	v_exp_f32_e32 v166, v166
	v_exp_f32_e32 v181, v151
	v_rcp_f32_e32 v190, v3
	v_add_f32_e32 v3, 1.0, v5
	v_rcp_f32_e32 v187, v3
	v_mul_f32_e32 v3, 0xbfb8aa3b, v189
	v_pk_add_f32 v[180:181], v[180:181], 1.0 op_sel_hi:[1,0]
	v_pk_add_f32 v[166:167], v[166:167], 1.0 op_sel_hi:[1,0]
	v_exp_f32_e32 v3, v3
	v_pk_mul_f32 v[166:167], v[166:167], v[170:171]
	v_pk_mul_f32 v[170:171], v[180:181], v[186:187]
	v_lshl_add_u64 v[160:161], v[160:161], 0, v[154:155]
	v_pk_mul_f32 v[92:93], v[92:93], v[170:171]
	v_pk_add_f32 v[170:171], v[172:173], 1.0 op_sel_hi:[1,0]
	v_add_f32_e32 v3, 1.0, v3
	v_pk_mul_f32 v[178:179], v[170:171], v[178:179]
	global_load_dwordx4 v[170:173], v[160:161], off
	v_mul_f32_e32 v5, 0xbfb8aa3b, v191
	v_rcp_f32_e32 v191, v3
	v_exp_f32_e32 v189, v5
	v_lshl_add_u64 v[152:153], v[152:153], 0, v[154:155]
	v_pk_mul_f32 v[90:91], v[90:91], v[166:167]
	v_pk_mul_f32 v[86:87], v[86:87], v[178:179]
	s_waitcnt vmcnt(2)
	v_lshlrev_b32_e32 v3, 16, v174
	v_mul_f32_e32 v3, 0xbfb8aa3b, v3
	v_and_b32_e32 v5, 0xffff0000, v174
	v_lshlrev_b32_e32 v151, 16, v175
	v_and_b32_e32 v181, 0xffff0000, v175
	v_lshlrev_b32_e32 v160, 16, v176
	v_and_b32_e32 v161, 0xffff0000, v176
	v_lshlrev_b32_e32 v186, 16, v177
	v_and_b32_e32 v187, 0xffff0000, v177
	global_load_dwordx4 v[174:177], v[152:153], off
	v_exp_f32_e32 v3, v3
	v_mul_f32_e32 v153, 0xbfb8aa3b, v160
	v_exp_f32_e32 v153, v153
	v_pk_add_f32 v[166:167], v[188:189], 1.0 op_sel_hi:[1,0]
	v_mul_f32_e32 v5, 0xbfb8aa3b, v5
	v_pk_mul_f32 v[166:167], v[166:167], v[190:191]
	s_waitcnt vmcnt(2)
	v_lshlrev_b32_e32 v178, 16, v184
	v_add_f32_e32 v3, 1.0, v3
	v_exp_f32_e32 v5, v5
	v_pk_mul_f32 v[88:89], v[88:89], v[166:167]
	v_lshlrev_b32_e32 v166, 16, v182
	v_rcp_f32_e32 v160, v3
	v_mul_f32_e32 v3, 0xbfb8aa3b, v178
	v_and_b32_e32 v167, 0xffff0000, v182
	v_mul_f32_e32 v152, 0xbfb8aa3b, v166
	v_exp_f32_e32 v166, v3
	v_add_f32_e32 v3, 1.0, v153
	v_rcp_f32_e32 v178, v3
	v_mul_f32_e32 v3, 0xbfb8aa3b, v167
	v_exp_f32_e32 v153, v3
	v_add_f32_e32 v3, 1.0, v5
	v_mul_f32_e32 v5, 0xbfb8aa3b, v161
	v_exp_f32_e32 v5, v5
	v_and_b32_e32 v179, 0xffff0000, v184
	v_rcp_f32_e32 v161, v3
	v_mul_f32_e32 v3, 0xbfb8aa3b, v179
	v_exp_f32_e32 v167, v3
	v_add_f32_e32 v3, 1.0, v5
	v_mul_f32_e32 v5, 0xbfb8aa3b, v151
	v_exp_f32_e32 v5, v5
	v_lshlrev_b32_e32 v180, 16, v183
	v_rcp_f32_e32 v179, v3
	v_mul_f32_e32 v3, 0xbfb8aa3b, v180
	v_exp_f32_e32 v180, v3
	v_add_f32_e32 v3, 1.0, v5
	v_mul_f32_e32 v5, 0xbfb8aa3b, v186
	v_exp_f32_e32 v5, v5
	v_lshlrev_b32_e32 v184, 16, v185
	v_rcp_f32_e32 v182, v3
	v_mul_f32_e32 v3, 0xbfb8aa3b, v184
	v_exp_f32_e32 v184, v3
	v_add_f32_e32 v3, 1.0, v5
	v_mul_f32_e32 v5, 0xbfb8aa3b, v181
	v_exp_f32_e32 v5, v5
	v_and_b32_e32 v183, 0xffff0000, v183
	v_mul_f32_e32 v151, 0xbfb8aa3b, v183
	v_rcp_f32_e32 v186, v3
	v_add_f32_e32 v3, 1.0, v5
	v_exp_f32_e32 v152, v152
	v_exp_f32_e32 v181, v151
	v_rcp_f32_e32 v183, v3
	v_mul_f32_e32 v3, 0xbfb8aa3b, v187
	v_exp_f32_e32 v3, v3
	v_and_b32_e32 v185, 0xffff0000, v185
	v_pk_add_f32 v[180:181], v[180:181], 1.0 op_sel_hi:[1,0]
	v_pk_add_f32 v[152:153], v[152:153], 1.0 op_sel_hi:[1,0]
	v_mul_f32_e32 v5, 0xbfb8aa3b, v185
	v_pk_mul_f32 v[152:153], v[152:153], v[160:161]
	v_pk_mul_f32 v[160:161], v[180:181], v[182:183]
	v_exp_f32_e32 v185, v5
	v_add_f32_e32 v3, 1.0, v3
	v_pk_mul_f32 v[116:117], v[116:117], v[160:161]
	v_rcp_f32_e32 v187, v3
	v_pk_add_f32 v[160:161], v[166:167], 1.0 op_sel_hi:[1,0]
	v_pk_mul_f32 v[114:115], v[114:115], v[152:153]
	v_pk_mul_f32 v[160:161], v[160:161], v[178:179]
	v_pk_add_f32 v[152:153], v[184:185], 1.0 op_sel_hi:[1,0]
	v_pk_mul_f32 v[110:111], v[110:111], v[160:161]
	v_mad_i64_i32 v[160:161], s[38:39], v150, s73, v[158:159]
	v_lshl_add_u64 v[166:167], v[160:161], 0, s[16:17]
	v_pk_mul_f32 v[152:153], v[152:153], v[186:187]
	v_lshl_add_u64 v[150:151], v[166:167], 0, v[156:157]
	v_pk_mul_f32 v[112:113], v[112:113], v[152:153]
	global_load_dwordx4 v[150:153], v[150:151], off
	s_waitcnt vmcnt(2)
	v_lshlrev_b32_e32 v3, 16, v170
	v_mul_f32_e32 v3, 0xbfb8aa3b, v3
	v_lshlrev_b32_e32 v184, 16, v172
	v_lshl_add_u64 v[160:161], v[160:161], 0, s[14:15]
	v_exp_f32_e32 v3, v3
	v_and_b32_e32 v5, 0xffff0000, v170
	v_lshlrev_b32_e32 v182, 16, v171
	v_and_b32_e32 v183, 0xffff0000, v171
	v_and_b32_e32 v185, 0xffff0000, v172
	v_lshl_add_u64 v[170:171], v[160:161], 0, v[156:157]
	v_mul_f32_e32 v172, 0xbfb8aa3b, v184
	v_lshlrev_b32_e32 v186, 16, v173
	global_load_dwordx4 v[178:181], v[170:171], off
	v_and_b32_e32 v187, 0xffff0000, v173
	s_waitcnt vmcnt(2)
	v_lshlrev_b32_e32 v188, 16, v175
	v_and_b32_e32 v189, 0xffff0000, v175
	v_lshlrev_b32_e32 v173, 16, v176
	v_and_b32_e32 v175, 0xffff0000, v176
	v_exp_f32_e32 v176, v172
	v_mul_f32_e32 v5, 0xbfb8aa3b, v5
	v_add_f32_e32 v3, 1.0, v3
	v_exp_f32_e32 v5, v5
	v_rcp_f32_e32 v172, v3
	v_mul_f32_e32 v3, 0xbfb8aa3b, v173
	v_lshlrev_b32_e32 v170, 16, v174
	v_and_b32_e32 v171, 0xffff0000, v174
	v_exp_f32_e32 v174, v3
	v_add_f32_e32 v3, 1.0, v176
	v_rcp_f32_e32 v176, v3
	v_mul_f32_e32 v3, 0xbfb8aa3b, v171
	v_exp_f32_e32 v171, v3
	v_add_f32_e32 v3, 1.0, v5
	v_mul_f32_e32 v5, 0xbfb8aa3b, v185
	v_exp_f32_e32 v5, v5
	v_rcp_f32_e32 v173, v3
	v_mul_f32_e32 v3, 0xbfb8aa3b, v175
	v_exp_f32_e32 v175, v3
	v_add_f32_e32 v3, 1.0, v5
	v_mul_f32_e32 v5, 0xbfb8aa3b, v182
	v_exp_f32_e32 v5, v5
	v_lshlrev_b32_e32 v190, 16, v177
	v_and_b32_e32 v191, 0xffff0000, v177
	v_rcp_f32_e32 v177, v3
	v_mul_f32_e32 v3, 0xbfb8aa3b, v188
	v_exp_f32_e32 v182, v3
	v_add_f32_e32 v3, 1.0, v5
	v_mul_f32_e32 v5, 0xbfb8aa3b, v186
	v_exp_f32_e32 v5, v5
	v_rcp_f32_e32 v184, v3
	v_mul_f32_e32 v3, 0xbfb8aa3b, v190
	v_exp_f32_e32 v186, v3
	v_add_f32_e32 v3, 1.0, v5
	v_mul_f32_e32 v5, 0xbfb8aa3b, v183
	v_exp_f32_e32 v5, v5
	v_rcp_f32_e32 v188, v3
	v_mul_f32_e32 v170, 0xbfb8aa3b, v170
	v_exp_f32_e32 v170, v170
	v_add_f32_e32 v3, 1.0, v5
	v_rcp_f32_e32 v185, v3
	v_mul_f32_e32 v3, 0xbfb8aa3b, v187
	v_exp_f32_e32 v3, v3
	v_mul_f32_e32 v183, 0xbfb8aa3b, v189
	v_exp_f32_e32 v183, v183
	v_mul_f32_e32 v5, 0xbfb8aa3b, v191
	v_exp_f32_e32 v187, v5
	v_add_f32_e32 v3, 1.0, v3
	v_rcp_f32_e32 v189, v3
	v_pk_add_f32 v[170:171], v[170:171], 1.0 op_sel_hi:[1,0]
	v_pk_add_f32 v[182:183], v[182:183], 1.0 op_sel_hi:[1,0]
	v_pk_mul_f32 v[170:171], v[170:171], v[172:173]
	v_pk_mul_f32 v[172:173], v[182:183], v[184:185]
	v_pk_mul_f32 v[82:83], v[82:83], v[170:171]
	v_pk_add_f32 v[170:171], v[186:187], 1.0 op_sel_hi:[1,0]
	v_pk_mul_f32 v[84:85], v[84:85], v[172:173]
	v_pk_add_f32 v[172:173], v[174:175], 1.0 op_sel_hi:[1,0]
	v_pk_mul_f32 v[170:171], v[170:171], v[188:189]
	v_lshl_add_u64 v[166:167], v[166:167], 0, v[154:155]
	v_pk_mul_f32 v[174:175], v[172:173], v[176:177]
	v_pk_mul_f32 v[80:81], v[80:81], v[170:171]
	global_load_dwordx4 v[170:173], v[166:167], off
	s_waitcnt vmcnt(2)
	v_lshlrev_b32_e32 v3, 16, v150
	v_and_b32_e32 v5, 0xffff0000, v150
	v_lshlrev_b32_e32 v177, 16, v151
	v_and_b32_e32 v183, 0xffff0000, v151
	v_lshl_add_u64 v[150:151], v[160:161], 0, v[154:155]
	v_lshlrev_b32_e32 v166, 16, v152
	v_and_b32_e32 v167, 0xffff0000, v152
	v_lshlrev_b32_e32 v182, 16, v153
	v_and_b32_e32 v185, 0xffff0000, v153
	global_load_dwordx4 v[150:153], v[150:151], off
	v_mul_f32_e32 v3, 0xbfb8aa3b, v3
	v_exp_f32_e32 v3, v3
	v_mul_f32_e32 v161, 0xbfb8aa3b, v166
	v_exp_f32_e32 v161, v161
	v_mul_f32_e32 v5, 0xbfb8aa3b, v5
	s_waitcnt vmcnt(2)
	v_lshlrev_b32_e32 v176, 16, v180
	v_add_f32_e32 v3, 1.0, v3
	v_exp_f32_e32 v5, v5
	v_pk_mul_f32 v[78:79], v[78:79], v[174:175]
	v_lshlrev_b32_e32 v174, 16, v178
	v_rcp_f32_e32 v166, v3
	v_mul_f32_e32 v3, 0xbfb8aa3b, v176
	v_and_b32_e32 v175, 0xffff0000, v178
	v_mul_f32_e32 v160, 0xbfb8aa3b, v174
	v_exp_f32_e32 v174, v3
	v_add_f32_e32 v3, 1.0, v161
	v_rcp_f32_e32 v176, v3
	v_mul_f32_e32 v3, 0xbfb8aa3b, v175
	v_exp_f32_e32 v161, v3
	v_add_f32_e32 v3, 1.0, v5
	v_mul_f32_e32 v5, 0xbfb8aa3b, v167
	v_exp_f32_e32 v5, v5
	v_and_b32_e32 v180, 0xffff0000, v180
	v_rcp_f32_e32 v167, v3
	v_mul_f32_e32 v3, 0xbfb8aa3b, v180
	v_exp_f32_e32 v175, v3
	v_add_f32_e32 v3, 1.0, v5
	v_mul_f32_e32 v5, 0xbfb8aa3b, v177
	v_exp_f32_e32 v5, v5
	v_lshlrev_b32_e32 v178, 16, v179
	v_rcp_f32_e32 v177, v3
	v_mul_f32_e32 v3, 0xbfb8aa3b, v178
	v_exp_f32_e32 v178, v3
	v_add_f32_e32 v3, 1.0, v5
	v_mul_f32_e32 v5, 0xbfb8aa3b, v182
	v_exp_f32_e32 v5, v5
	v_lshlrev_b32_e32 v184, 16, v181
	v_rcp_f32_e32 v180, v3
	v_mul_f32_e32 v3, 0xbfb8aa3b, v184
	v_exp_f32_e32 v182, v3
	v_add_f32_e32 v3, 1.0, v5
	v_mul_f32_e32 v5, 0xbfb8aa3b, v183
	v_exp_f32_e32 v5, v5
	v_rcp_f32_e32 v184, v3
	v_and_b32_e32 v186, 0xffff0000, v181
	v_and_b32_e32 v179, 0xffff0000, v179
	v_add_f32_e32 v3, 1.0, v5
	v_rcp_f32_e32 v181, v3
	v_mul_f32_e32 v3, 0xbfb8aa3b, v185
	v_exp_f32_e32 v3, v3
	v_exp_f32_e32 v160, v160
	v_mul_f32_e32 v179, 0xbfb8aa3b, v179
	v_mul_f32_e32 v5, 0xbfb8aa3b, v186
	v_exp_f32_e32 v179, v179
	v_exp_f32_e32 v183, v5
	v_add_f32_e32 v3, 1.0, v3
	v_rcp_f32_e32 v185, v3
	v_pk_add_f32 v[160:161], v[160:161], 1.0 op_sel_hi:[1,0]
	v_pk_add_f32 v[178:179], v[178:179], 1.0 op_sel_hi:[1,0]
	v_pk_mul_f32 v[160:161], v[160:161], v[166:167]
	v_pk_mul_f32 v[166:167], v[178:179], v[180:181]
	v_pk_mul_f32 v[106:107], v[106:107], v[160:161]
	v_pk_add_f32 v[160:161], v[182:183], 1.0 op_sel_hi:[1,0]
	v_pk_mul_f32 v[108:109], v[108:109], v[166:167]
	v_pk_mul_f32 v[160:161], v[160:161], v[184:185]
	v_pk_add_f32 v[166:167], v[174:175], 1.0 op_sel_hi:[1,0]
	v_pk_mul_f32 v[104:105], v[104:105], v[160:161]
	v_add_u32_e32 v160, 0x80, v4
	v_pk_mul_f32 v[166:167], v[166:167], v[176:177]
	v_mad_i64_i32 v[160:161], s[38:39], v160, s73, v[158:159]
	v_pk_mul_f32 v[102:103], v[102:103], v[166:167]
	s_waitcnt vmcnt(1)
	v_lshlrev_b32_e32 v3, 16, v170
	v_lshl_add_u64 v[166:167], v[160:161], 0, s[16:17]
	v_lshl_add_u64 v[174:175], v[166:167], 0, v[156:157]
	v_lshl_add_u64 v[160:161], v[160:161], 0, s[14:15]
	v_mul_f32_e32 v3, 0xbfb8aa3b, v3
	v_and_b32_e32 v5, 0xffff0000, v170
	global_load_dwordx4 v[174:177], v[174:175], off
	v_lshlrev_b32_e32 v182, 16, v171
	v_and_b32_e32 v183, 0xffff0000, v171
	v_lshlrev_b32_e32 v184, 16, v172
	v_lshl_add_u64 v[170:171], v[160:161], 0, v[156:157]
	v_exp_f32_e32 v3, v3
	v_lshlrev_b32_e32 v186, 16, v173
	global_load_dwordx4 v[178:181], v[170:171], off
	v_and_b32_e32 v187, 0xffff0000, v173
	s_waitcnt vmcnt(2)
	v_lshlrev_b32_e32 v188, 16, v151
	v_and_b32_e32 v189, 0xffff0000, v151
	v_lshlrev_b32_e32 v151, 16, v152
	v_and_b32_e32 v173, 0xffff0000, v152
	v_mul_f32_e32 v152, 0xbfb8aa3b, v184
	v_lshlrev_b32_e32 v190, 16, v153
	v_and_b32_e32 v191, 0xffff0000, v153
	v_exp_f32_e32 v153, v152
	v_mul_f32_e32 v5, 0xbfb8aa3b, v5
	v_add_f32_e32 v3, 1.0, v3
	v_exp_f32_e32 v5, v5
	v_lshlrev_b32_e32 v170, 16, v150
	v_rcp_f32_e32 v152, v3
	v_mul_f32_e32 v3, 0xbfb8aa3b, v151
	v_and_b32_e32 v171, 0xffff0000, v150
	v_mul_f32_e32 v150, 0xbfb8aa3b, v170
	v_exp_f32_e32 v170, v3
	v_add_f32_e32 v3, 1.0, v153
	v_and_b32_e32 v185, 0xffff0000, v172
	v_rcp_f32_e32 v172, v3
	v_mul_f32_e32 v3, 0xbfb8aa3b, v171
	v_exp_f32_e32 v151, v3
	v_add_f32_e32 v3, 1.0, v5
	v_mul_f32_e32 v5, 0xbfb8aa3b, v185
	v_exp_f32_e32 v5, v5
	v_rcp_f32_e32 v153, v3
	v_mul_f32_e32 v3, 0xbfb8aa3b, v173
	v_exp_f32_e32 v171, v3
	v_add_f32_e32 v3, 1.0, v5
	v_mul_f32_e32 v5, 0xbfb8aa3b, v182
	v_exp_f32_e32 v5, v5
	v_rcp_f32_e32 v173, v3
	v_mul_f32_e32 v3, 0xbfb8aa3b, v188
	v_exp_f32_e32 v182, v3
	v_add_f32_e32 v3, 1.0, v5
	v_mul_f32_e32 v5, 0xbfb8aa3b, v186
	v_exp_f32_e32 v5, v5
	v_rcp_f32_e32 v184, v3
	v_mul_f32_e32 v3, 0xbfb8aa3b, v190
	v_exp_f32_e32 v186, v3
	v_add_f32_e32 v3, 1.0, v5
	v_mul_f32_e32 v5, 0xbfb8aa3b, v183
	v_exp_f32_e32 v5, v5
	v_rcp_f32_e32 v188, v3
	v_exp_f32_e32 v150, v150
	v_mul_f32_e32 v183, 0xbfb8aa3b, v189
	v_add_f32_e32 v3, 1.0, v5
	v_rcp_f32_e32 v185, v3
	v_mul_f32_e32 v3, 0xbfb8aa3b, v187
	v_exp_f32_e32 v3, v3
	v_mul_f32_e32 v5, 0xbfb8aa3b, v191
	v_exp_f32_e32 v183, v183
	v_exp_f32_e32 v187, v5
	v_add_f32_e32 v3, 1.0, v3
	v_rcp_f32_e32 v189, v3
	v_pk_add_f32 v[150:151], v[150:151], 1.0 op_sel_hi:[1,0]
	v_pk_add_f32 v[182:183], v[182:183], 1.0 op_sel_hi:[1,0]
	v_pk_mul_f32 v[150:151], v[150:151], v[152:153]
	v_pk_mul_f32 v[152:153], v[182:183], v[184:185]
	v_pk_mul_f32 v[74:75], v[74:75], v[150:151]
	v_pk_add_f32 v[150:151], v[186:187], 1.0 op_sel_hi:[1,0]
	v_pk_mul_f32 v[76:77], v[76:77], v[152:153]
	v_pk_mul_f32 v[150:151], v[150:151], v[188:189]
	v_pk_add_f32 v[152:153], v[170:171], 1.0 op_sel_hi:[1,0]
	v_pk_mul_f32 v[72:73], v[72:73], v[150:151]
	v_lshl_add_u64 v[150:151], v[166:167], 0, v[154:155]
	v_pk_mul_f32 v[170:171], v[152:153], v[172:173]
	global_load_dwordx4 v[150:153], v[150:151], off
	v_lshl_add_u64 v[160:161], v[160:161], 0, v[154:155]
	v_pk_mul_f32 v[70:71], v[70:71], v[170:171]
	global_load_dwordx4 v[170:173], v[160:161], off
	s_waitcnt vmcnt(3)
	v_lshlrev_b32_e32 v3, 16, v174
	v_mul_f32_e32 v3, 0xbfb8aa3b, v3
	v_lshlrev_b32_e32 v166, 16, v176
	v_exp_f32_e32 v3, v3
	v_mul_f32_e32 v161, 0xbfb8aa3b, v166
	v_and_b32_e32 v5, 0xffff0000, v174
	v_exp_f32_e32 v161, v161
	v_mul_f32_e32 v5, 0xbfb8aa3b, v5
	v_and_b32_e32 v167, 0xffff0000, v176
	s_waitcnt vmcnt(2)
	v_lshlrev_b32_e32 v176, 16, v180
	v_add_f32_e32 v3, 1.0, v3
	v_exp_f32_e32 v5, v5
	v_lshlrev_b32_e32 v174, 16, v178
	v_rcp_f32_e32 v166, v3
	v_mul_f32_e32 v3, 0xbfb8aa3b, v176
	v_lshlrev_b32_e32 v182, 16, v175
	v_and_b32_e32 v183, 0xffff0000, v175
	v_and_b32_e32 v175, 0xffff0000, v178
	v_mul_f32_e32 v160, 0xbfb8aa3b, v174
	v_exp_f32_e32 v174, v3
	v_add_f32_e32 v3, 1.0, v161
	v_rcp_f32_e32 v176, v3
	v_mul_f32_e32 v3, 0xbfb8aa3b, v175
	v_exp_f32_e32 v161, v3
	v_add_f32_e32 v3, 1.0, v5
	v_mul_f32_e32 v5, 0xbfb8aa3b, v167
	v_exp_f32_e32 v5, v5
	v_lshlrev_b32_e32 v184, 16, v177
	v_and_b32_e32 v185, 0xffff0000, v177
	v_and_b32_e32 v177, 0xffff0000, v180
	v_rcp_f32_e32 v167, v3
	v_mul_f32_e32 v3, 0xbfb8aa3b, v177
	v_exp_f32_e32 v175, v3
	v_add_f32_e32 v3, 1.0, v5
	v_mul_f32_e32 v5, 0xbfb8aa3b, v182
	v_exp_f32_e32 v5, v5
	v_lshlrev_b32_e32 v178, 16, v179
	v_rcp_f32_e32 v177, v3
	v_mul_f32_e32 v3, 0xbfb8aa3b, v178
	v_exp_f32_e32 v178, v3
	v_add_f32_e32 v3, 1.0, v5
	v_mul_f32_e32 v5, 0xbfb8aa3b, v184
	v_exp_f32_e32 v5, v5
	v_lshlrev_b32_e32 v186, 16, v181
	v_rcp_f32_e32 v180, v3
	v_mul_f32_e32 v3, 0xbfb8aa3b, v186
	v_exp_f32_e32 v182, v3
	v_add_f32_e32 v3, 1.0, v5
	v_mul_f32_e32 v5, 0xbfb8aa3b, v183
	v_exp_f32_e32 v5, v5
	v_rcp_f32_e32 v184, v3
	v_and_b32_e32 v187, 0xffff0000, v181
	v_and_b32_e32 v179, 0xffff0000, v179
	v_add_f32_e32 v3, 1.0, v5
	v_rcp_f32_e32 v181, v3
	v_mul_f32_e32 v3, 0xbfb8aa3b, v185
	v_exp_f32_e32 v3, v3
	v_exp_f32_e32 v160, v160
	v_mul_f32_e32 v179, 0xbfb8aa3b, v179
	v_exp_f32_e32 v179, v179
	v_mul_f32_e32 v5, 0xbfb8aa3b, v187
	v_exp_f32_e32 v183, v5
	v_add_f32_e32 v3, 1.0, v3
	v_rcp_f32_e32 v185, v3
	v_pk_add_f32 v[160:161], v[160:161], 1.0 op_sel_hi:[1,0]
	v_pk_add_f32 v[178:179], v[178:179], 1.0 op_sel_hi:[1,0]
	v_pk_mul_f32 v[160:161], v[160:161], v[166:167]
	v_pk_mul_f32 v[166:167], v[178:179], v[180:181]
	v_pk_mul_f32 v[66:67], v[66:67], v[160:161]
	v_pk_add_f32 v[160:161], v[182:183], 1.0 op_sel_hi:[1,0]
	v_pk_mul_f32 v[68:69], v[68:69], v[166:167]
	v_pk_add_f32 v[166:167], v[174:175], 1.0 op_sel_hi:[1,0]
	v_pk_mul_f32 v[160:161], v[160:161], v[184:185]
	v_pk_mul_f32 v[166:167], v[166:167], v[176:177]
	v_pk_mul_f32 v[64:65], v[64:65], v[160:161]
	v_pk_mul_f32 v[62:63], v[62:63], v[166:167]
	s_waitcnt vmcnt(1)
	v_lshlrev_b32_e32 v3, 16, v150
	v_and_b32_e32 v5, 0xffff0000, v150
	v_add_u32_e32 v150, 0x90, v4
	v_mad_i64_i32 v[160:161], s[38:39], v150, s73, v[158:159]
	v_lshl_add_u64 v[166:167], v[160:161], 0, s[16:17]
	v_lshl_add_u64 v[174:175], v[166:167], 0, v[156:157]
	v_mul_f32_e32 v3, 0xbfb8aa3b, v3
	global_load_dwordx4 v[174:177], v[174:175], off
	v_lshlrev_b32_e32 v184, 16, v152
	v_exp_f32_e32 v3, v3
	v_and_b32_e32 v185, 0xffff0000, v152
	v_mul_f32_e32 v152, 0xbfb8aa3b, v184
	v_lshlrev_b32_e32 v186, 16, v153
	v_and_b32_e32 v187, 0xffff0000, v153
	s_waitcnt vmcnt(1)
	v_lshlrev_b32_e32 v188, 16, v171
	v_and_b32_e32 v189, 0xffff0000, v171
	v_lshlrev_b32_e32 v153, 16, v172
	v_and_b32_e32 v171, 0xffff0000, v172
	v_exp_f32_e32 v172, v152
	v_mul_f32_e32 v5, 0xbfb8aa3b, v5
	v_lshl_add_u64 v[160:161], v[160:161], 0, s[14:15]
	v_add_f32_e32 v3, 1.0, v3
	v_exp_f32_e32 v5, v5
	v_lshlrev_b32_e32 v182, 16, v151
	v_and_b32_e32 v183, 0xffff0000, v151
	v_lshl_add_u64 v[150:151], v[160:161], 0, v[156:157]
	v_rcp_f32_e32 v152, v3
	v_mul_f32_e32 v3, 0xbfb8aa3b, v153
	global_load_dwordx4 v[178:181], v[150:151], off
	v_lshlrev_b32_e32 v150, 16, v170
	v_and_b32_e32 v151, 0xffff0000, v170
	v_exp_f32_e32 v170, v3
	v_add_f32_e32 v3, 1.0, v172
	v_rcp_f32_e32 v172, v3
	v_mul_f32_e32 v3, 0xbfb8aa3b, v151
	v_exp_f32_e32 v151, v3
	v_add_f32_e32 v3, 1.0, v5
	v_mul_f32_e32 v5, 0xbfb8aa3b, v185
	v_exp_f32_e32 v5, v5
	v_rcp_f32_e32 v153, v3
	v_mul_f32_e32 v3, 0xbfb8aa3b, v171
	v_exp_f32_e32 v171, v3
	v_add_f32_e32 v3, 1.0, v5
	v_mul_f32_e32 v5, 0xbfb8aa3b, v182
	v_exp_f32_e32 v5, v5
	v_lshlrev_b32_e32 v190, 16, v173
	v_and_b32_e32 v191, 0xffff0000, v173
	v_rcp_f32_e32 v173, v3
	v_mul_f32_e32 v3, 0xbfb8aa3b, v188
	v_exp_f32_e32 v182, v3
	v_add_f32_e32 v3, 1.0, v5
	v_mul_f32_e32 v5, 0xbfb8aa3b, v186
	v_exp_f32_e32 v5, v5
	v_rcp_f32_e32 v184, v3
	v_mul_f32_e32 v3, 0xbfb8aa3b, v190
	v_exp_f32_e32 v186, v3
	v_add_f32_e32 v3, 1.0, v5
	v_mul_f32_e32 v5, 0xbfb8aa3b, v183
	v_exp_f32_e32 v5, v5
	v_rcp_f32_e32 v188, v3
	v_mul_f32_e32 v150, 0xbfb8aa3b, v150
	v_exp_f32_e32 v150, v150
	v_add_f32_e32 v3, 1.0, v5
	v_rcp_f32_e32 v185, v3
	v_mul_f32_e32 v3, 0xbfb8aa3b, v187
	v_exp_f32_e32 v3, v3
	v_mul_f32_e32 v183, 0xbfb8aa3b, v189
	v_mul_f32_e32 v5, 0xbfb8aa3b, v191
	v_exp_f32_e32 v183, v183
	v_exp_f32_e32 v187, v5
	v_add_f32_e32 v3, 1.0, v3
	v_rcp_f32_e32 v189, v3
	v_pk_add_f32 v[150:151], v[150:151], 1.0 op_sel_hi:[1,0]
	v_pk_add_f32 v[182:183], v[182:183], 1.0 op_sel_hi:[1,0]
	v_pk_mul_f32 v[150:151], v[150:151], v[152:153]
	v_pk_mul_f32 v[152:153], v[182:183], v[184:185]
	v_pk_mul_f32 v[34:35], v[34:35], v[150:151]
	v_pk_add_f32 v[150:151], v[186:187], 1.0 op_sel_hi:[1,0]
	v_pk_mul_f32 v[36:37], v[36:37], v[152:153]
	v_pk_mul_f32 v[150:151], v[150:151], v[188:189]
	v_pk_add_f32 v[152:153], v[170:171], 1.0 op_sel_hi:[1,0]
	v_pk_mul_f32 v[32:33], v[32:33], v[150:151]
	v_lshl_add_u64 v[150:151], v[166:167], 0, v[154:155]
	v_pk_mul_f32 v[170:171], v[152:153], v[172:173]
	global_load_dwordx4 v[150:153], v[150:151], off
	v_lshl_add_u64 v[160:161], v[160:161], 0, v[154:155]
	v_pk_mul_f32 v[30:31], v[30:31], v[170:171]
	global_load_dwordx4 v[170:173], v[160:161], off
	s_waitcnt vmcnt(3)
	v_lshlrev_b32_e32 v3, 16, v174
	v_mul_f32_e32 v3, 0xbfb8aa3b, v3
	v_lshlrev_b32_e32 v166, 16, v176
	v_exp_f32_e32 v3, v3
	v_mul_f32_e32 v161, 0xbfb8aa3b, v166
	v_and_b32_e32 v5, 0xffff0000, v174
	v_exp_f32_e32 v161, v161
	v_mul_f32_e32 v5, 0xbfb8aa3b, v5
	v_and_b32_e32 v167, 0xffff0000, v176
	v_add_f32_e32 v3, 1.0, v3
	v_exp_f32_e32 v5, v5
	v_rcp_f32_e32 v166, v3
	v_lshlrev_b32_e32 v182, 16, v175
	v_and_b32_e32 v183, 0xffff0000, v175
	v_lshlrev_b32_e32 v184, 16, v177
	v_and_b32_e32 v185, 0xffff0000, v177
	s_waitcnt vmcnt(2)
	v_lshlrev_b32_e32 v176, 16, v180
	v_lshlrev_b32_e32 v174, 16, v178
	v_mul_f32_e32 v3, 0xbfb8aa3b, v176
	v_and_b32_e32 v175, 0xffff0000, v178
	v_mul_f32_e32 v160, 0xbfb8aa3b, v174
	v_exp_f32_e32 v174, v3
	v_add_f32_e32 v3, 1.0, v161
	v_rcp_f32_e32 v176, v3
	v_mul_f32_e32 v3, 0xbfb8aa3b, v175
	v_exp_f32_e32 v161, v3
	v_add_f32_e32 v3, 1.0, v5
	v_mul_f32_e32 v5, 0xbfb8aa3b, v167
	v_exp_f32_e32 v5, v5
	v_and_b32_e32 v177, 0xffff0000, v180
	v_rcp_f32_e32 v167, v3
	v_mul_f32_e32 v3, 0xbfb8aa3b, v177
	v_exp_f32_e32 v175, v3
	v_add_f32_e32 v3, 1.0, v5
	v_mul_f32_e32 v5, 0xbfb8aa3b, v182
	v_exp_f32_e32 v5, v5
	v_lshlrev_b32_e32 v178, 16, v179
	v_rcp_f32_e32 v177, v3
	v_mul_f32_e32 v3, 0xbfb8aa3b, v178
	v_exp_f32_e32 v178, v3
	v_add_f32_e32 v3, 1.0, v5
	v_mul_f32_e32 v5, 0xbfb8aa3b, v184
	v_exp_f32_e32 v5, v5
	v_lshlrev_b32_e32 v186, 16, v181
	v_rcp_f32_e32 v180, v3
	v_mul_f32_e32 v3, 0xbfb8aa3b, v186
	v_exp_f32_e32 v182, v3
	v_add_f32_e32 v3, 1.0, v5
	v_mul_f32_e32 v5, 0xbfb8aa3b, v183
	v_exp_f32_e32 v5, v5
	v_rcp_f32_e32 v184, v3
	v_and_b32_e32 v187, 0xffff0000, v181
	v_and_b32_e32 v179, 0xffff0000, v179
	v_add_f32_e32 v3, 1.0, v5
	v_rcp_f32_e32 v181, v3
	v_mul_f32_e32 v3, 0xbfb8aa3b, v185
	v_exp_f32_e32 v3, v3
	v_exp_f32_e32 v160, v160
	v_mul_f32_e32 v179, 0xbfb8aa3b, v179
	v_exp_f32_e32 v179, v179
	v_mul_f32_e32 v5, 0xbfb8aa3b, v187
	v_exp_f32_e32 v183, v5
	v_add_f32_e32 v3, 1.0, v3
	v_rcp_f32_e32 v185, v3
	v_pk_add_f32 v[160:161], v[160:161], 1.0 op_sel_hi:[1,0]
	v_pk_add_f32 v[178:179], v[178:179], 1.0 op_sel_hi:[1,0]
	v_pk_mul_f32 v[160:161], v[160:161], v[166:167]
	v_pk_mul_f32 v[166:167], v[178:179], v[180:181]
	v_pk_mul_f32 v[58:59], v[58:59], v[160:161]
	v_pk_add_f32 v[160:161], v[182:183], 1.0 op_sel_hi:[1,0]
	v_pk_mul_f32 v[60:61], v[60:61], v[166:167]
	v_pk_add_f32 v[166:167], v[174:175], 1.0 op_sel_hi:[1,0]
	v_pk_mul_f32 v[160:161], v[160:161], v[184:185]
	s_waitcnt vmcnt(1)
	v_lshlrev_b32_e32 v3, 16, v150
	v_and_b32_e32 v5, 0xffff0000, v150
	v_add_u32_e32 v150, 0xa0, v4
	v_pk_mul_f32 v[166:167], v[166:167], v[176:177]
	v_pk_mul_f32 v[56:57], v[56:57], v[160:161]
	v_mad_i64_i32 v[160:161], s[38:39], v150, s73, v[158:159]
	v_pk_mul_f32 v[54:55], v[54:55], v[166:167]
	v_lshl_add_u64 v[166:167], v[160:161], 0, s[16:17]
	v_lshl_add_u64 v[174:175], v[166:167], 0, v[156:157]
	global_load_dwordx4 v[174:177], v[174:175], off
	v_mul_f32_e32 v3, 0xbfb8aa3b, v3
	v_lshlrev_b32_e32 v184, 16, v152
	v_exp_f32_e32 v3, v3
	v_and_b32_e32 v185, 0xffff0000, v152
	v_mul_f32_e32 v152, 0xbfb8aa3b, v184
	v_lshlrev_b32_e32 v186, 16, v153
	v_and_b32_e32 v187, 0xffff0000, v153
	s_waitcnt vmcnt(1)
	v_lshlrev_b32_e32 v188, 16, v171
	v_and_b32_e32 v189, 0xffff0000, v171
	v_lshlrev_b32_e32 v153, 16, v172
	v_and_b32_e32 v171, 0xffff0000, v172
	v_exp_f32_e32 v172, v152
	v_lshl_add_u64 v[160:161], v[160:161], 0, s[14:15]
	v_mul_f32_e32 v5, 0xbfb8aa3b, v5
	v_lshlrev_b32_e32 v182, 16, v151
	v_and_b32_e32 v183, 0xffff0000, v151
	v_lshl_add_u64 v[150:151], v[160:161], 0, v[156:157]
	v_add_f32_e32 v3, 1.0, v3
	v_exp_f32_e32 v5, v5
	global_load_dwordx4 v[178:181], v[150:151], off
	v_rcp_f32_e32 v152, v3
	v_mul_f32_e32 v3, 0xbfb8aa3b, v153
	v_lshlrev_b32_e32 v150, 16, v170
	v_and_b32_e32 v151, 0xffff0000, v170
	v_exp_f32_e32 v170, v3
	v_add_f32_e32 v3, 1.0, v172
	v_rcp_f32_e32 v172, v3
	v_mul_f32_e32 v3, 0xbfb8aa3b, v151
	v_exp_f32_e32 v151, v3
	v_add_f32_e32 v3, 1.0, v5
	v_mul_f32_e32 v5, 0xbfb8aa3b, v185
	v_exp_f32_e32 v5, v5
	v_rcp_f32_e32 v153, v3
	v_mul_f32_e32 v3, 0xbfb8aa3b, v171
	v_exp_f32_e32 v171, v3
	v_add_f32_e32 v3, 1.0, v5
	v_mul_f32_e32 v5, 0xbfb8aa3b, v182
	v_exp_f32_e32 v5, v5
	v_lshlrev_b32_e32 v190, 16, v173
	v_and_b32_e32 v191, 0xffff0000, v173
	v_rcp_f32_e32 v173, v3
	v_mul_f32_e32 v3, 0xbfb8aa3b, v188
	v_exp_f32_e32 v182, v3
	v_add_f32_e32 v3, 1.0, v5
	v_mul_f32_e32 v5, 0xbfb8aa3b, v186
	v_exp_f32_e32 v5, v5
	v_rcp_f32_e32 v184, v3
	v_mul_f32_e32 v3, 0xbfb8aa3b, v190
	v_exp_f32_e32 v186, v3
	v_add_f32_e32 v3, 1.0, v5
	v_mul_f32_e32 v5, 0xbfb8aa3b, v183
	v_exp_f32_e32 v5, v5
	v_rcp_f32_e32 v188, v3
	v_mul_f32_e32 v150, 0xbfb8aa3b, v150
	v_exp_f32_e32 v150, v150
	v_add_f32_e32 v3, 1.0, v5
	v_rcp_f32_e32 v185, v3
	v_mul_f32_e32 v3, 0xbfb8aa3b, v187
	v_exp_f32_e32 v3, v3
	v_mul_f32_e32 v183, 0xbfb8aa3b, v189
	v_mul_f32_e32 v5, 0xbfb8aa3b, v191
	v_exp_f32_e32 v183, v183
	v_exp_f32_e32 v187, v5
	v_add_f32_e32 v3, 1.0, v3
	v_rcp_f32_e32 v189, v3
	v_pk_add_f32 v[150:151], v[150:151], 1.0 op_sel_hi:[1,0]
	v_pk_add_f32 v[182:183], v[182:183], 1.0 op_sel_hi:[1,0]
	v_pk_mul_f32 v[150:151], v[150:151], v[152:153]
	v_pk_mul_f32 v[152:153], v[182:183], v[184:185]
	v_pk_mul_f32 v[26:27], v[26:27], v[150:151]
	v_pk_add_f32 v[150:151], v[186:187], 1.0 op_sel_hi:[1,0]
	v_pk_mul_f32 v[28:29], v[28:29], v[152:153]
	v_pk_mul_f32 v[150:151], v[150:151], v[188:189]
	v_pk_add_f32 v[152:153], v[170:171], 1.0 op_sel_hi:[1,0]
	v_pk_mul_f32 v[24:25], v[24:25], v[150:151]
	v_lshl_add_u64 v[150:151], v[166:167], 0, v[154:155]
	v_pk_mul_f32 v[170:171], v[152:153], v[172:173]
	global_load_dwordx4 v[150:153], v[150:151], off
	v_lshl_add_u64 v[160:161], v[160:161], 0, v[154:155]
	v_pk_mul_f32 v[22:23], v[22:23], v[170:171]
	global_load_dwordx4 v[170:173], v[160:161], off
	s_waitcnt vmcnt(3)
	v_lshlrev_b32_e32 v3, 16, v174
	v_mul_f32_e32 v3, 0xbfb8aa3b, v3
	v_lshlrev_b32_e32 v166, 16, v176
	v_exp_f32_e32 v3, v3
	v_mul_f32_e32 v166, 0xbfb8aa3b, v166
	v_and_b32_e32 v5, 0xffff0000, v174
	v_and_b32_e32 v167, 0xffff0000, v176
	v_exp_f32_e32 v176, v166
	v_mul_f32_e32 v5, 0xbfb8aa3b, v5
	v_add_f32_e32 v3, 1.0, v3
	v_exp_f32_e32 v5, v5
	v_rcp_f32_e32 v166, v3
	v_lshlrev_b32_e32 v182, 16, v175
	v_and_b32_e32 v183, 0xffff0000, v175
	v_lshlrev_b32_e32 v184, 16, v177
	v_and_b32_e32 v185, 0xffff0000, v177
	v_add_u32_e32 v4, 0xb0, v4
	s_waitcnt vmcnt(2)
	v_lshlrev_b32_e32 v161, 16, v180
	v_lshlrev_b32_e32 v174, 16, v178
	v_mul_f32_e32 v3, 0xbfb8aa3b, v161
	v_and_b32_e32 v175, 0xffff0000, v178
	v_mul_f32_e32 v160, 0xbfb8aa3b, v174
	v_exp_f32_e32 v174, v3
	v_add_f32_e32 v3, 1.0, v176
	v_rcp_f32_e32 v176, v3
	v_mul_f32_e32 v3, 0xbfb8aa3b, v175
	v_exp_f32_e32 v161, v3
	v_add_f32_e32 v3, 1.0, v5
	v_mul_f32_e32 v5, 0xbfb8aa3b, v167
	v_exp_f32_e32 v5, v5
	v_and_b32_e32 v177, 0xffff0000, v180
	v_rcp_f32_e32 v167, v3
	v_mul_f32_e32 v3, 0xbfb8aa3b, v177
	v_exp_f32_e32 v175, v3
	v_add_f32_e32 v3, 1.0, v5
	v_mul_f32_e32 v5, 0xbfb8aa3b, v182
	v_exp_f32_e32 v5, v5
	v_lshlrev_b32_e32 v178, 16, v179
	v_rcp_f32_e32 v177, v3
	v_mul_f32_e32 v3, 0xbfb8aa3b, v178
	v_exp_f32_e32 v178, v3
	v_add_f32_e32 v3, 1.0, v5
	v_mul_f32_e32 v5, 0xbfb8aa3b, v184
	v_exp_f32_e32 v5, v5
	v_lshlrev_b32_e32 v186, 16, v181
	v_rcp_f32_e32 v180, v3
	v_mul_f32_e32 v3, 0xbfb8aa3b, v186
	v_exp_f32_e32 v182, v3
	v_add_f32_e32 v3, 1.0, v5
	v_mul_f32_e32 v5, 0xbfb8aa3b, v183
	v_exp_f32_e32 v5, v5
	v_and_b32_e32 v179, 0xffff0000, v179
	v_rcp_f32_e32 v184, v3
	v_and_b32_e32 v187, 0xffff0000, v181
	v_add_f32_e32 v3, 1.0, v5
	v_mul_f32_e32 v179, 0xbfb8aa3b, v179
	v_rcp_f32_e32 v181, v3
	v_mul_f32_e32 v3, 0xbfb8aa3b, v185
	v_exp_f32_e32 v160, v160
	v_exp_f32_e32 v179, v179
	v_exp_f32_e32 v3, v3
	v_mul_f32_e32 v5, 0xbfb8aa3b, v187
	v_pk_add_f32 v[160:161], v[160:161], 1.0 op_sel_hi:[1,0]
	v_pk_add_f32 v[178:179], v[178:179], 1.0 op_sel_hi:[1,0]
	v_exp_f32_e32 v183, v5
	v_add_f32_e32 v3, 1.0, v3
	v_pk_mul_f32 v[160:161], v[160:161], v[166:167]
	v_pk_mul_f32 v[166:167], v[178:179], v[180:181]
	v_rcp_f32_e32 v185, v3
	v_pk_mul_f32 v[52:53], v[52:53], v[166:167]
	v_pk_add_f32 v[166:167], v[174:175], 1.0 op_sel_hi:[1,0]
	v_mad_i64_i32 v[4:5], s[38:39], v4, s73, v[158:159]
	v_pk_mul_f32 v[166:167], v[166:167], v[176:177]
	v_pk_mul_f32 v[50:51], v[50:51], v[160:161]
	v_pk_add_f32 v[160:161], v[182:183], 1.0 op_sel_hi:[1,0]
	v_pk_mul_f32 v[46:47], v[46:47], v[166:167]
	v_lshl_add_u64 v[166:167], v[4:5], 0, s[16:17]
	v_pk_mul_f32 v[160:161], v[160:161], v[184:185]
	v_lshl_add_u64 v[158:159], v[166:167], 0, v[156:157]
	v_pk_mul_f32 v[48:49], v[48:49], v[160:161]
	global_load_dwordx4 v[158:161], v[158:159], off
	s_waitcnt vmcnt(2)
	v_lshlrev_b32_e32 v3, 16, v150
	v_mul_f32_e32 v3, 0xbfb8aa3b, v3
	v_exp_f32_e32 v3, v3
	v_lshlrev_b32_e32 v176, 16, v152
	v_lshl_add_u64 v[4:5], v[4:5], 0, s[14:15]
	v_and_b32_e32 v174, 0xffff0000, v150
	v_lshlrev_b32_e32 v175, 16, v151
	v_and_b32_e32 v177, 0xffff0000, v151
	s_waitcnt vmcnt(1)
	v_lshlrev_b32_e32 v180, 16, v170
	v_lshl_add_u64 v[150:151], v[4:5], 0, v[156:157]
	v_and_b32_e32 v157, 0xffff0000, v170
	v_mul_f32_e32 v170, 0xbfb8aa3b, v176
	v_lshlrev_b32_e32 v182, 16, v171
	v_and_b32_e32 v183, 0xffff0000, v171
	v_lshlrev_b32_e32 v171, 16, v172
	v_lshlrev_b32_e32 v185, 16, v173
	v_and_b32_e32 v186, 0xffff0000, v173
	v_add_f32_e32 v3, 1.0, v3
	v_exp_f32_e32 v173, v170
	v_rcp_f32_e32 v170, v3
	v_mul_f32_e32 v3, 0xbfb8aa3b, v171
	v_mul_f32_e32 v171, 0xbfb8aa3b, v174
	v_exp_f32_e32 v171, v171
	v_and_b32_e32 v178, 0xffff0000, v152
	v_lshlrev_b32_e32 v179, 16, v153
	v_and_b32_e32 v181, 0xffff0000, v153
	global_load_dwordx4 v[150:153], v[150:151], off
	v_and_b32_e32 v184, 0xffff0000, v172
	v_exp_f32_e32 v172, v3
	v_add_f32_e32 v3, 1.0, v173
	v_rcp_f32_e32 v174, v3
	v_mul_f32_e32 v3, 0xbfb8aa3b, v157
	v_exp_f32_e32 v157, v3
	v_add_f32_e32 v3, 1.0, v171
	v_mul_f32_e32 v171, 0xbfb8aa3b, v178
	v_exp_f32_e32 v176, v171
	v_mul_f32_e32 v175, 0xbfb8aa3b, v175
	v_exp_f32_e32 v178, v175
	v_rcp_f32_e32 v171, v3
	v_mul_f32_e32 v3, 0xbfb8aa3b, v184
	v_exp_f32_e32 v173, v3
	v_add_f32_e32 v3, 1.0, v176
	v_rcp_f32_e32 v175, v3
	v_mul_f32_e32 v3, 0xbfb8aa3b, v182
	v_exp_f32_e32 v176, v3
	v_add_f32_e32 v3, 1.0, v178
	v_mul_f32_e32 v178, 0xbfb8aa3b, v179
	v_exp_f32_e32 v179, v178
	v_rcp_f32_e32 v178, v3
	v_mul_f32_e32 v3, 0xbfb8aa3b, v185
	v_mul_f32_e32 v177, 0xbfb8aa3b, v177
	v_mul_f32_e32 v156, 0xbfb8aa3b, v180
	v_exp_f32_e32 v180, v3
	v_add_f32_e32 v3, 1.0, v179
	v_exp_f32_e32 v179, v177
	v_mul_f32_e32 v177, 0xbfb8aa3b, v183
	v_exp_f32_e32 v156, v156
	v_exp_f32_e32 v177, v177
	v_rcp_f32_e32 v182, v3
	v_add_f32_e32 v3, 1.0, v179
	v_rcp_f32_e32 v179, v3
	v_mul_f32_e32 v3, 0xbfb8aa3b, v181
	v_exp_f32_e32 v3, v3
	v_pk_add_f32 v[176:177], v[176:177], 1.0 op_sel_hi:[1,0]
	v_pk_add_f32 v[156:157], v[156:157], 1.0 op_sel_hi:[1,0]
	v_lshl_add_u64 v[4:5], v[4:5], 0, v[154:155]
	v_pk_mul_f32 v[156:157], v[156:157], v[170:171]
	v_pk_mul_f32 v[170:171], v[176:177], v[178:179]
	v_add_f32_e32 v3, 1.0, v3
	v_pk_mul_f32 v[20:21], v[20:21], v[170:171]
	v_mul_f32_e32 v170, 0xbfb8aa3b, v186
	v_exp_f32_e32 v181, v170
	v_rcp_f32_e32 v183, v3
	v_pk_mul_f32 v[18:19], v[18:19], v[156:157]
	v_pk_add_f32 v[170:171], v[172:173], 1.0 op_sel_hi:[1,0]
	v_pk_add_f32 v[156:157], v[180:181], 1.0 op_sel_hi:[1,0]
	v_pk_mul_f32 v[174:175], v[170:171], v[174:175]
	v_pk_mul_f32 v[156:157], v[156:157], v[182:183]
	v_pk_mul_f32 v[14:15], v[14:15], v[174:175]
	v_pk_mul_f32 v[16:17], v[16:17], v[156:157]
	v_lshl_add_u64 v[156:157], v[166:167], 0, v[154:155]
	global_load_dwordx4 v[170:173], v[156:157], off
	s_waitcnt vmcnt(2)
	v_lshlrev_b32_e32 v3, 16, v158
	global_load_dwordx4 v[154:157], v[4:5], off
	v_mul_f32_e32 v3, 0xbfb8aa3b, v3
	v_exp_f32_e32 v3, v3
	v_lshlrev_b32_e32 v166, 16, v159
	v_and_b32_e32 v167, 0xffff0000, v159
	v_lshlrev_b32_e32 v159, 16, v160
	v_and_b32_e32 v158, 0xffff0000, v158
	v_lshlrev_b32_e32 v174, 16, v161
	v_and_b32_e32 v175, 0xffff0000, v161
	v_add_f32_e32 v3, 1.0, v3
	v_and_b32_e32 v160, 0xffff0000, v160
	s_waitcnt vmcnt(2)
	v_lshlrev_b32_e32 v4, 16, v150
	v_and_b32_e32 v5, 0xffff0000, v150
	v_mul_f32_e32 v150, 0xbfb8aa3b, v159
	v_lshlrev_b32_e32 v161, 16, v151
	v_and_b32_e32 v176, 0xffff0000, v151
	v_lshlrev_b32_e32 v151, 16, v152
	v_lshlrev_b32_e32 v178, 16, v153
	v_and_b32_e32 v179, 0xffff0000, v153
	v_exp_f32_e32 v153, v150
	v_rcp_f32_e32 v150, v3
	v_mul_f32_e32 v3, 0xbfb8aa3b, v151
	v_mul_f32_e32 v151, 0xbfb8aa3b, v158
	v_exp_f32_e32 v151, v151
	v_and_b32_e32 v177, 0xffff0000, v152
	v_exp_f32_e32 v152, v3
	v_add_f32_e32 v3, 1.0, v153
	v_rcp_f32_e32 v158, v3
	v_mul_f32_e32 v3, 0xbfb8aa3b, v5
	v_exp_f32_e32 v5, v3
	v_add_f32_e32 v3, 1.0, v151
	v_mul_f32_e32 v151, 0xbfb8aa3b, v160
	v_exp_f32_e32 v159, v151
	v_rcp_f32_e32 v151, v3
	v_mul_f32_e32 v3, 0xbfb8aa3b, v177
	v_exp_f32_e32 v153, v3
	v_add_f32_e32 v3, 1.0, v159
	v_mul_f32_e32 v159, 0xbfb8aa3b, v166
	v_exp_f32_e32 v166, v159
	v_rcp_f32_e32 v159, v3
	v_mul_f32_e32 v3, 0xbfb8aa3b, v161
	v_mul_f32_e32 v161, 0xbfb8aa3b, v174
	v_exp_f32_e32 v161, v161
	v_exp_f32_e32 v160, v3
	v_add_f32_e32 v3, 1.0, v166
	v_rcp_f32_e32 v166, v3
	v_mul_f32_e32 v3, 0xbfb8aa3b, v178
	v_exp_f32_e32 v174, v3
	v_add_f32_e32 v3, 1.0, v161
	v_mul_f32_e32 v161, 0xbfb8aa3b, v167
	v_exp_f32_e32 v167, v161
	v_mul_f32_e32 v4, 0xbfb8aa3b, v4
	v_mul_f32_e32 v161, 0xbfb8aa3b, v176
	v_exp_f32_e32 v4, v4
	v_exp_f32_e32 v161, v161
	v_rcp_f32_e32 v176, v3
	v_add_f32_e32 v3, 1.0, v167
	v_rcp_f32_e32 v167, v3
	v_mul_f32_e32 v3, 0xbfb8aa3b, v175
	v_exp_f32_e32 v3, v3
	v_pk_add_f32 v[160:161], v[160:161], 1.0 op_sel_hi:[1,0]
	v_pk_add_f32 v[4:5], v[4:5], 1.0 op_sel_hi:[1,0]
	v_add_f32_e32 v3, 1.0, v3
	v_pk_mul_f32 v[4:5], v[4:5], v[150:151]
	v_pk_mul_f32 v[150:151], v[160:161], v[166:167]
	v_rcp_f32_e32 v177, v3
	v_pk_mul_f32 v[44:45], v[44:45], v[150:151]
	v_mul_f32_e32 v150, 0xbfb8aa3b, v179
	v_exp_f32_e32 v175, v150
	v_pk_add_f32 v[150:151], v[152:153], 1.0 op_sel_hi:[1,0]
	s_waitcnt vmcnt(1)
	v_lshlrev_b32_e32 v3, 16, v170
	v_pk_mul_f32 v[150:151], v[150:151], v[158:159]
	v_mul_f32_e32 v3, 0xbfb8aa3b, v3
	v_pk_mul_f32 v[42:43], v[42:43], v[4:5]
	v_pk_add_f32 v[4:5], v[174:175], 1.0 op_sel_hi:[1,0]
	v_pk_mul_f32 v[38:39], v[38:39], v[150:151]
	v_lshlrev_b32_e32 v150, 16, v172
	v_exp_f32_e32 v3, v3
	v_pk_mul_f32 v[4:5], v[4:5], v[176:177]
	v_mul_f32_e32 v150, 0xbfb8aa3b, v150
	v_pk_mul_f32 v[40:41], v[40:41], v[4:5]
	v_and_b32_e32 v5, 0xffff0000, v170
	s_waitcnt vmcnt(0)
	v_lshlrev_b32_e32 v4, 16, v154
	v_and_b32_e32 v153, 0xffff0000, v154
	v_exp_f32_e32 v154, v150
	v_mul_f32_e32 v5, 0xbfb8aa3b, v5
	v_lshlrev_b32_e32 v166, 16, v155
	v_and_b32_e32 v167, 0xffff0000, v155
	v_lshlrev_b32_e32 v152, 16, v156
	v_and_b32_e32 v155, 0xffff0000, v156
	v_add_f32_e32 v3, 1.0, v3
	v_exp_f32_e32 v156, v5
	v_rcp_f32_e32 v150, v3
	v_mul_f32_e32 v3, 0xbfb8aa3b, v152
	v_and_b32_e32 v151, 0xffff0000, v172
	v_exp_f32_e32 v152, v3
	v_add_f32_e32 v3, 1.0, v154
	v_rcp_f32_e32 v154, v3
	v_mul_f32_e32 v3, 0xbfb8aa3b, v153
	v_mul_f32_e32 v151, 0xbfb8aa3b, v151
	v_lshlrev_b32_e32 v158, 16, v171
	v_exp_f32_e32 v5, v3
	v_add_f32_e32 v3, 1.0, v156
	v_exp_f32_e32 v156, v151
	v_rcp_f32_e32 v151, v3
	v_mul_f32_e32 v3, 0xbfb8aa3b, v155
	v_mul_f32_e32 v155, 0xbfb8aa3b, v158
	v_and_b32_e32 v159, 0xffff0000, v171
	v_lshlrev_b32_e32 v170, 16, v157
	v_and_b32_e32 v171, 0xffff0000, v157
	v_exp_f32_e32 v157, v155
	v_exp_f32_e32 v153, v3
	v_add_f32_e32 v3, 1.0, v156
	v_lshlrev_b32_e32 v160, 16, v173
	v_rcp_f32_e32 v155, v3
	v_mul_f32_e32 v3, 0xbfb8aa3b, v166
	v_exp_f32_e32 v156, v3
	v_add_f32_e32 v3, 1.0, v157
	v_mul_f32_e32 v157, 0xbfb8aa3b, v160
	v_exp_f32_e32 v157, v157
	v_rcp_f32_e32 v158, v3
	v_mul_f32_e32 v3, 0xbfb8aa3b, v170
	v_exp_f32_e32 v160, v3
	v_add_f32_e32 v3, 1.0, v157
	v_mul_f32_e32 v157, 0xbfb8aa3b, v159
	v_exp_f32_e32 v159, v157
	v_mul_f32_e32 v4, 0xbfb8aa3b, v4
	v_mul_f32_e32 v157, 0xbfb8aa3b, v167
	v_exp_f32_e32 v4, v4
	v_exp_f32_e32 v157, v157
	v_rcp_f32_e32 v166, v3
	v_add_f32_e32 v3, 1.0, v159
	v_and_b32_e32 v161, 0xffff0000, v173
	v_rcp_f32_e32 v159, v3
	v_mul_f32_e32 v3, 0xbfb8aa3b, v161
	v_exp_f32_e32 v3, v3
	v_pk_add_f32 v[156:157], v[156:157], 1.0 op_sel_hi:[1,0]
	v_pk_add_f32 v[4:5], v[4:5], 1.0 op_sel_hi:[1,0]
	v_add_f32_e32 v3, 1.0, v3
	v_pk_mul_f32 v[4:5], v[4:5], v[150:151]
	v_pk_mul_f32 v[150:151], v[156:157], v[158:159]
	v_rcp_f32_e32 v167, v3
	v_pk_mul_f32 v[12:13], v[12:13], v[150:151]
	v_mul_f32_e32 v150, 0xbfb8aa3b, v171
	v_exp_f32_e32 v161, v150
	v_pk_mul_f32 v[10:11], v[10:11], v[4:5]
	v_pk_add_f32 v[150:151], v[152:153], 1.0 op_sel_hi:[1,0]
	v_pk_add_f32 v[4:5], v[160:161], 1.0 op_sel_hi:[1,0]
	v_pk_mul_f32 v[150:151], v[150:151], v[154:155]
	v_pk_mul_f32 v[4:5], v[4:5], v[166:167]
	v_pk_mul_f32 v[6:7], v[6:7], v[150:151]
	v_pk_mul_f32 v[8:9], v[8:9], v[4:5]
